# attention B/C loops: persistent -mref block as MFMA C operand (no per-tile v_mov init), overflow check without ds_bpermute; GU K-loop counted vmcnt waits
# speedup vs baseline: 1.0257x; 1.0257x over previous
.LBB0_53:
	s_mul_hi_i32 s2, s10, 0x2e8ba2e9
	s_lshr_b32 s3, s2, 31
	s_ashr_i32 s2, s2, 5
	s_add_i32 s17, s2, s3
	s_lshl_b32 s2, s17, 3
	s_sub_i32 s3, s0, s2
	s_min_i32 s3, s3, 8
	s_abs_i32 s14, s3
	v_cvt_f32_u32_e32 v2, s14
	s_sub_i32 s19, 0, s14
	s_mul_i32 s15, s17, 0xffffff50
	s_add_i32 s15, s15, s10
	v_rcp_iflag_f32_e32 v2, v2
	s_abs_i32 s16, s15
	s_xor_b32 s18, s15, s3
	s_ashr_i32 s18, s18, 31
	v_mul_f32_e32 v2, 0x4f7ffffe, v2
	v_cvt_u32_f32_e32 v2, v2
	s_mulk_i32 s17, 0xa8
	s_mov_b32 s4, 0x308d000
	s_mov_b32 s6, 0x30ad000
	v_readfirstlane_b32 s22, v2
	s_mul_i32 s19, s19, s22
	s_mul_hi_u32 s19, s22, s19
	s_add_i32 s22, s22, s19
	s_mul_hi_u32 s19, s16, s22
	s_mul_i32 s22, s19, s14
	s_sub_i32 s16, s16, s22
	s_add_i32 s23, s19, 1
	s_sub_i32 s22, s16, s14
	s_cmp_ge_u32 s16, s14
	s_cselect_b32 s19, s23, s19
	s_cselect_b32 s16, s22, s16
	s_add_i32 s22, s19, 1
	s_cmp_ge_u32 s16, s14
	s_cselect_b32 s14, s22, s19
	s_xor_b32 s14, s14, s18
	s_sub_i32 s16, s14, s18
	s_mul_i32 s18, s16, s3
	s_add_i32 s15, s15, s2
	s_sub_i32 s2, s15, s18
	s_lshl_b32 s14, s2, 8
	v_add_u32_e32 v2, s14, v164
	v_ashrrev_i32_e32 v3, 31, v2
	v_lshlrev_b64 v[2:3], 11, v[2:3]
	s_lshl_b32 s15, s16, 8
	v_lshl_add_u64 v[52:53], v[168:169], 0, v[2:3]
	s_mov_b32 s2, 0x20000
	v_add_u32_e32 v4, s15, v164
	v_add_co_u32_e32 v54, vcc, s2, v52
	v_ashrrev_i32_e32 v5, 31, v4
	s_nop 0
	v_addc_co_u32_e32 v55, vcc, 0, v53, vcc
	s_mov_b32 s3, 0x40000
	v_lshlrev_b64 v[48:49], 11, v[4:5]
	v_add_co_u32_e32 v56, vcc, s3, v52
	v_lshl_add_u64 v[50:51], v[166:167], 0, v[48:49]
	s_nop 0
	v_addc_co_u32_e32 v57, vcc, 0, v53, vcc
	v_add_co_u32_e32 v58, vcc, s2, v50
	s_mov_b32 s2, 0x60000
	s_nop 0
	v_addc_co_u32_e32 v59, vcc, 0, v51, vcc
	v_add_co_u32_e32 v60, vcc, s3, v50
	global_load_dwordx4 v[16:19], v[52:53], off
	global_load_dwordx4 v[20:23], v[54:55], off
	v_addc_co_u32_e32 v61, vcc, 0, v51, vcc
	v_add_co_u32_e32 v62, vcc, s2, v50
	global_load_dwordx4 v[24:27], v[56:57], off
	global_load_dwordx4 v[28:31], v[50:51], off
	v_addc_co_u32_e32 v63, vcc, 0, v51, vcc
	v_add_co_u32_e32 v64, vcc, s2, v52
	global_load_dwordx4 v[32:35], v[58:59], off
	v_addc_co_u32_e32 v65, vcc, 0, v53, vcc
	global_load_dwordx4 v[36:39], v[60:61], off
	global_load_dwordx4 v[40:43], v[62:63], off
	global_load_dwordx4 v[44:47], v[64:65], off
	global_load_dwordx4 v[146:149], v[52:53], off offset:128
	global_load_dwordx4 v[150:153], v[54:55], off offset:128
	global_load_dwordx4 v[158:161], v[56:57], off offset:128
	global_load_dwordx4 v[154:157], v[64:65], off offset:128
	global_load_dwordx4 v[130:133], v[50:51], off offset:128
	global_load_dwordx4 v[142:145], v[58:59], off offset:128
	global_load_dwordx4 v[134:137], v[60:61], off offset:128
	global_load_dwordx4 v[138:141], v[62:63], off offset:128
	s_sub_i32 s18, s10, s18
	s_sub_i32 s17, s18, s17
	s_lshl_b32 s18, s17, 8
	s_ashr_i32 s19, s18, 31
	v_lshl_add_u64 v[178:179], v[174:175], 0, v[48:49]
	v_lshl_add_u64 v[48:49], v[164:165], 0, s[18:19]
	v_mov_b32_e32 v2, 0
	v_lshlrev_b64 v[48:49], 11, v[48:49]
	s_mov_b32 s16, 1
	s_mov_b64 s[2:3], 0
	v_mov_b32_e32 v3, v2
	v_mov_b32_e32 v4, v2
	v_mov_b32_e32 v5, v2
	v_mov_b32_e32 v6, v2
	v_mov_b32_e32 v7, v2
	v_mov_b32_e32 v8, v2
	v_mov_b32_e32 v9, v2
	v_mov_b32_e32 v10, v2
	v_mov_b32_e32 v11, v2
	v_mov_b32_e32 v12, v2
	v_mov_b32_e32 v13, v2
	v_mov_b32_e32 v14, v2
	v_mov_b32_e32 v15, v2
	v_lshl_add_u64 v[180:181], v[176:177], 0, v[48:49]
	v_mov_b32_e32 v48, v2
	v_mov_b32_e32 v49, v2
	v_mov_b32_e32 v50, v2
	v_mov_b32_e32 v51, v2
	v_mov_b32_e32 v52, v2
	v_mov_b32_e32 v53, v2
	v_mov_b32_e32 v54, v2
	v_mov_b32_e32 v55, v2
	v_mov_b32_e32 v56, v2
	v_mov_b32_e32 v57, v2
	v_mov_b32_e32 v58, v2
	v_mov_b32_e32 v59, v2
	v_mov_b32_e32 v60, v2
	v_mov_b32_e32 v61, v2
	v_mov_b32_e32 v62, v2
	v_mov_b32_e32 v63, v2
	s_waitcnt vmcnt(12)
	ds_write_b128 v172, v[28:31] offset:36864
	s_waitcnt vmcnt(11)
	ds_write_b128 v172, v[32:35] offset:46080
	s_waitcnt vmcnt(9)
	ds_write_b128 v172, v[36:39] offset:55296
	s_waitcnt vmcnt(8)
	ds_write_b128 v172, v[40:43] offset:64512
	ds_write_b128 v172, v[16:19]
	ds_write_b128 v172, v[20:23] offset:9216
	ds_write_b128 v172, v[24:27] offset:18432
	s_waitcnt vmcnt(7)
	ds_write_b128 v172, v[44:47] offset:27648
	v_mov_b32_e32 v16, v2
	v_mov_b32_e32 v17, v2
	v_mov_b32_e32 v34, v2
	v_mov_b32_e32 v35, v2
	v_mov_b32_e32 v36, v2
	v_mov_b32_e32 v37, v2
	v_mov_b32_e32 v38, v2
	v_mov_b32_e32 v39, v2
	v_mov_b32_e32 v40, v2
	v_mov_b32_e32 v41, v2
	v_mov_b32_e32 v42, v2
	v_mov_b32_e32 v43, v2
	v_mov_b32_e32 v44, v2
	v_mov_b32_e32 v45, v2
	v_mov_b32_e32 v46, v2
	v_mov_b32_e32 v47, v2
	v_mov_b32_e32 v18, v2
	v_mov_b32_e32 v19, v2
	v_mov_b32_e32 v20, v2
	v_mov_b32_e32 v21, v2
	v_mov_b32_e32 v22, v2
	v_mov_b32_e32 v23, v2
	v_mov_b32_e32 v24, v2
	v_mov_b32_e32 v25, v2
	v_mov_b32_e32 v26, v2
	v_mov_b32_e32 v27, v2
	v_mov_b32_e32 v28, v2
	v_mov_b32_e32 v29, v2
	v_mov_b32_e32 v30, v2
	v_mov_b32_e32 v31, v2
	v_mov_b32_e32 v32, v2
	v_mov_b32_e32 v33, v2
	v_mov_b32_e32 v64, v2
	v_mov_b32_e32 v65, v2
	v_mov_b32_e32 v66, v2
	v_mov_b32_e32 v67, v2
	v_mov_b32_e32 v68, v2
	v_mov_b32_e32 v69, v2
	v_mov_b32_e32 v70, v2
	v_mov_b32_e32 v71, v2
	v_mov_b32_e32 v72, v2
	v_mov_b32_e32 v73, v2
	v_mov_b32_e32 v74, v2
	v_mov_b32_e32 v75, v2
	v_mov_b32_e32 v76, v2
	v_mov_b32_e32 v77, v2
	v_mov_b32_e32 v78, v2
	v_mov_b32_e32 v79, v2
	v_mov_b32_e32 v80, v2
	v_mov_b32_e32 v81, v2
	v_mov_b32_e32 v98, v2
	v_mov_b32_e32 v99, v2
	v_mov_b32_e32 v100, v2
	v_mov_b32_e32 v101, v2
	v_mov_b32_e32 v102, v2
	v_mov_b32_e32 v103, v2
	v_mov_b32_e32 v104, v2
	v_mov_b32_e32 v105, v2
	v_mov_b32_e32 v106, v2
	v_mov_b32_e32 v107, v2
	v_mov_b32_e32 v108, v2
	v_mov_b32_e32 v109, v2
	v_mov_b32_e32 v110, v2
	v_mov_b32_e32 v111, v2
	v_mov_b32_e32 v112, v2
	v_mov_b32_e32 v113, v2
	v_mov_b32_e32 v82, v2
	v_mov_b32_e32 v83, v2
	v_mov_b32_e32 v84, v2
	v_mov_b32_e32 v85, v2
	v_mov_b32_e32 v86, v2
	v_mov_b32_e32 v87, v2
	v_mov_b32_e32 v88, v2
	v_mov_b32_e32 v89, v2
	v_mov_b32_e32 v90, v2
	v_mov_b32_e32 v91, v2
	v_mov_b32_e32 v92, v2
	v_mov_b32_e32 v93, v2
	v_mov_b32_e32 v94, v2
	v_mov_b32_e32 v95, v2
	v_mov_b32_e32 v96, v2
	v_mov_b32_e32 v97, v2
	v_mov_b32_e32 v114, v2
	v_mov_b32_e32 v115, v2
	v_mov_b32_e32 v116, v2
	v_mov_b32_e32 v117, v2
	v_mov_b32_e32 v118, v2
	v_mov_b32_e32 v119, v2
	v_mov_b32_e32 v120, v2
	v_mov_b32_e32 v121, v2
	v_mov_b32_e32 v122, v2
	v_mov_b32_e32 v123, v2
	v_mov_b32_e32 v124, v2
	v_mov_b32_e32 v125, v2
	v_mov_b32_e32 v126, v2
	v_mov_b32_e32 v127, v2
	v_mov_b32_e32 v128, v2
	v_mov_b32_e32 v129, v2
	s_mov_b32 s7, 0x30cd000
	s_waitcnt lgkmcnt(0)
	s_barrier
.LBB0_54:
	s_bitcmp1_b32 s16, 0
	s_cselect_b32 s17, 0, 0x12000
	v_add_u32_e32 v203, s17, v171
	ds_read_b128 v[192:195], v203 offset:36864
	v_add_u32_e32 v204, s17, v170
	ds_read_b128 v[196:199], v204
	ds_read_b128 v[208:211], v204 offset:4608
	ds_read_b128 v[218:221], v204 offset:9216
	ds_read_b128 v[222:225], v204 offset:13824
	s_waitcnt lgkmcnt(3)
	v_mfma_f32_32x32x16_bf16 v[114:129], v[192:195], v[196:199], v[114:129]
	s_waitcnt lgkmcnt(2)
	v_mfma_f32_32x32x16_bf16 v[82:97], v[192:195], v[208:211], v[82:97]
	s_waitcnt lgkmcnt(1)
	v_mfma_f32_32x32x16_bf16 v[50:65], v[192:195], v[218:221], v[50:65]
	s_waitcnt lgkmcnt(0)
	v_mfma_f32_32x32x16_bf16 v[18:33], v[192:195], v[222:225], v[18:33]
	ds_read_b128 v[192:195], v203 offset:41472
	s_waitcnt lgkmcnt(0)
	v_mfma_f32_32x32x16_bf16 v[98:113], v[192:195], v[196:199], v[98:113]
	v_mfma_f32_32x32x16_bf16 v[66:81], v[192:195], v[208:211], v[66:81]
	v_mfma_f32_32x32x16_bf16 v[34:49], v[192:195], v[218:221], v[34:49]
	v_mfma_f32_32x32x16_bf16 v[2:17], v[192:195], v[222:225], v[2:17]
	s_cselect_b32 s17, 0x12000, 0
	v_add_u32_e32 v196, s17, v172
	s_waitcnt vmcnt(7)
	ds_write_b128 v196, v[146:149]
	s_waitcnt vmcnt(4)
	ds_write_b128 v196, v[150:153] offset:9216
	ds_write_b128 v196, v[158:161] offset:18432
	ds_write_b128 v196, v[154:157] offset:27648
	ds_read_b128 v[146:149], v203 offset:36896
	ds_read_b128 v[150:153], v204 offset:32
	ds_read_b128 v[154:157], v204 offset:4640
	ds_read_b128 v[158:161], v204 offset:9248
	ds_read_b128 v[192:195], v204 offset:13856
	s_waitcnt lgkmcnt(3)
	v_mfma_f32_32x32x16_bf16 v[114:129], v[146:149], v[150:153], v[114:129]
	s_waitcnt lgkmcnt(2)
	v_mfma_f32_32x32x16_bf16 v[82:97], v[146:149], v[154:157], v[82:97]
	s_waitcnt lgkmcnt(1)
	v_mfma_f32_32x32x16_bf16 v[50:65], v[146:149], v[158:161], v[50:65]
	s_waitcnt lgkmcnt(0)
	v_mfma_f32_32x32x16_bf16 v[18:33], v[146:149], v[192:195], v[18:33]
	ds_read_b128 v[146:149], v203 offset:41504
	s_waitcnt lgkmcnt(0)
	v_mfma_f32_32x32x16_bf16 v[98:113], v[146:149], v[150:153], v[98:113]
	v_mfma_f32_32x32x16_bf16 v[66:81], v[146:149], v[154:157], v[66:81]
	v_mfma_f32_32x32x16_bf16 v[34:49], v[146:149], v[158:161], v[34:49]
	v_mfma_f32_32x32x16_bf16 v[2:17], v[146:149], v[192:195], v[2:17]
	s_waitcnt vmcnt(0)
	ds_write_b128 v196, v[130:133] offset:36864
	ds_write_b128 v196, v[142:145] offset:46080
	ds_write_b128 v196, v[134:137] offset:55296
	ds_write_b128 v196, v[138:141] offset:64512
	ds_read_b128 v[130:133], v203 offset:36928
	ds_read_b128 v[134:137], v204 offset:64
	ds_read_b128 v[138:141], v204 offset:4672
	ds_read_b128 v[142:145], v203 offset:41536
	ds_read_b128 v[154:157], v204 offset:9280
	ds_read_b128 v[192:195], v204 offset:13888
	s_waitcnt lgkmcnt(4)
	v_mfma_f32_32x32x16_bf16 v[114:129], v[130:133], v[134:137], v[114:129]
	s_waitcnt lgkmcnt(3)
	v_mfma_f32_32x32x16_bf16 v[82:97], v[130:133], v[138:141], v[82:97]
	s_waitcnt lgkmcnt(1)
	v_mfma_f32_32x32x16_bf16 v[50:65], v[130:133], v[154:157], v[50:65]
	s_waitcnt lgkmcnt(0)
	v_mfma_f32_32x32x16_bf16 v[18:33], v[130:133], v[192:195], v[18:33]
	v_lshl_add_u64 v[130:131], v[180:181], 0, s[2:3]
	v_add_co_u32_e32 v132, vcc, s4, v130
	s_nop 1
	v_addc_co_u32_e32 v133, vcc, 0, v131, vcc
	v_mfma_f32_32x32x16_bf16 v[98:113], v[142:145], v[134:137], v[98:113]
	v_add_co_u32_e32 v134, vcc, s6, v130
	s_nop 1
	v_addc_co_u32_e32 v135, vcc, 0, v131, vcc
	global_load_dwordx4 v[146:149], v[132:133], off offset:2304
	global_load_dwordx4 v[150:153], v[134:135], off offset:2304
	v_add_co_u32_e32 v132, vcc, s7, v130
	v_mfma_f32_32x32x16_bf16 v[34:49], v[142:145], v[154:157], v[34:49]
	s_nop 0
	v_addc_co_u32_e32 v133, vcc, 0, v131, vcc
	v_add_co_u32_e32 v130, vcc, s73, v130
	s_nop 1
	v_addc_co_u32_e32 v131, vcc, 0, v131, vcc
	global_load_dwordx4 v[158:161], v[132:133], off offset:2304
	global_load_dwordx4 v[154:157], v[130:131], off offset:2304
	v_mfma_f32_32x32x16_bf16 v[66:81], v[142:145], v[138:141], v[66:81]
	v_mfma_f32_32x32x16_bf16 v[2:17], v[142:145], v[192:195], v[2:17]
	ds_read_b128 v[130:133], v203 offset:36960
	ds_read_b128 v[134:137], v204 offset:96
	ds_read_b128 v[138:141], v204 offset:4704
	ds_read_b128 v[192:195], v203 offset:41568
	ds_read_b128 v[196:199], v204 offset:9312
	ds_read_b128 v[208:211], v204 offset:13920
	s_mov_b32 s17, 0xc6d000
	s_waitcnt lgkmcnt(4)
	v_mfma_f32_32x32x16_bf16 v[114:129], v[130:133], v[134:137], v[114:129]
	s_waitcnt lgkmcnt(3)
	v_mfma_f32_32x32x16_bf16 v[82:97], v[130:133], v[138:141], v[82:97]
	s_waitcnt lgkmcnt(1)
	v_mfma_f32_32x32x16_bf16 v[50:65], v[130:133], v[196:199], v[50:65]
	s_waitcnt lgkmcnt(0)
	v_mfma_f32_32x32x16_bf16 v[18:33], v[130:133], v[208:211], v[18:33]
	v_lshl_add_u64 v[130:131], v[178:179], 0, s[2:3]
	v_add_co_u32_e32 v132, vcc, s17, v130
	s_mov_b32 s17, 0xc8d000
	s_nop 0
	v_addc_co_u32_e32 v133, vcc, 0, v131, vcc
	s_add_u32 s2, s2, 0x80
	v_mfma_f32_32x32x16_bf16 v[98:113], v[192:195], v[134:137], v[98:113]
	v_add_co_u32_e32 v134, vcc, s17, v130
	s_mov_b32 s17, 0xcad000
	s_nop 0
	v_addc_co_u32_e32 v135, vcc, 0, v131, vcc
	v_add_co_u32_e32 v136, vcc, s17, v130
	s_mov_b32 s17, 0xccd000
	s_nop 0
	v_addc_co_u32_e32 v137, vcc, 0, v131, vcc
	v_mfma_f32_32x32x16_bf16 v[66:81], v[192:195], v[138:141], v[66:81]
	v_add_co_u32_e32 v138, vcc, s17, v130
	s_addc_u32 s3, s3, 0
	s_nop 0
	v_addc_co_u32_e32 v139, vcc, 0, v131, vcc
	global_load_dwordx4 v[130:133], v[132:133], off offset:2304
	s_nop 0
	global_load_dwordx4 v[142:145], v[134:135], off offset:2304
	s_nop 0
	global_load_dwordx4 v[134:137], v[136:137], off offset:2304
	s_add_i32 s16, s16, 1
	global_load_dwordx4 v[138:141], v[138:139], off offset:2304
	v_mfma_f32_32x32x16_bf16 v[34:49], v[192:195], v[196:199], v[34:49]
	s_cmpk_lg_i32 s2, 0x700
	s_barrier
	v_mfma_f32_32x32x16_bf16 v[2:17], v[192:195], v[208:211], v[2:17]
	s_cbranch_scc1 .LBB0_54
	ds_read_b128 v[178:181], v171 offset:36864
	ds_read_b128 v[192:195], v170
	ds_read_b128 v[196:199], v170 offset:4608
	ds_read_b128 v[208:211], v170 offset:9216
	ds_read_b128 v[218:221], v170 offset:13824
	s_waitcnt lgkmcnt(3)
	v_mfma_f32_32x32x16_bf16 v[114:129], v[178:181], v[192:195], v[114:129]
	s_waitcnt lgkmcnt(2)
	v_mfma_f32_32x32x16_bf16 v[82:97], v[178:181], v[196:199], v[82:97]
	s_waitcnt lgkmcnt(1)
	v_mfma_f32_32x32x16_bf16 v[50:65], v[178:181], v[208:211], v[50:65]
	s_waitcnt lgkmcnt(0)
	v_mfma_f32_32x32x16_bf16 v[18:33], v[178:181], v[218:221], v[18:33]
	ds_read_b128 v[178:181], v171 offset:41472
	s_waitcnt lgkmcnt(0)
	v_mfma_f32_32x32x16_bf16 v[98:113], v[178:181], v[192:195], v[98:113]
	v_mfma_f32_32x32x16_bf16 v[66:81], v[178:181], v[196:199], v[66:81]
	v_mfma_f32_32x32x16_bf16 v[34:49], v[178:181], v[208:211], v[34:49]
	v_mfma_f32_32x32x16_bf16 v[2:17], v[178:181], v[218:221], v[2:17]
	s_waitcnt vmcnt(7)
	ds_write_b128 v183, v[146:149]
	s_waitcnt vmcnt(6)
	ds_write_b128 v186, v[150:153]
	s_waitcnt vmcnt(5)
	ds_write_b128 v185, v[158:161]
	s_waitcnt vmcnt(4)
	ds_write_b128 v184, v[154:157]
	ds_read_b128 v[146:149], v171 offset:36896
	ds_read_b128 v[150:153], v170 offset:32
	ds_read_b128 v[154:157], v170 offset:4640
	ds_read_b128 v[158:161], v170 offset:9248
	ds_read_b128 v[178:181], v170 offset:13856
	s_waitcnt lgkmcnt(3)
	v_mfma_f32_32x32x16_bf16 v[114:129], v[146:149], v[150:153], v[114:129]
	s_waitcnt lgkmcnt(2)
	v_mfma_f32_32x32x16_bf16 v[82:97], v[146:149], v[154:157], v[82:97]
	s_waitcnt lgkmcnt(1)
	v_mfma_f32_32x32x16_bf16 v[50:65], v[146:149], v[158:161], v[50:65]
	s_waitcnt lgkmcnt(0)
	v_mfma_f32_32x32x16_bf16 v[18:33], v[146:149], v[178:181], v[18:33]
	ds_read_b128 v[146:149], v171 offset:41504
	s_waitcnt lgkmcnt(0)
	v_mfma_f32_32x32x16_bf16 v[98:113], v[146:149], v[150:153], v[98:113]
	v_mfma_f32_32x32x16_bf16 v[66:81], v[146:149], v[154:157], v[66:81]
	v_mfma_f32_32x32x16_bf16 v[34:49], v[146:149], v[158:161], v[34:49]
	v_mfma_f32_32x32x16_bf16 v[2:17], v[146:149], v[178:181], v[2:17]
	s_waitcnt vmcnt(3)
	ds_write_b128 v190, v[130:133]
	s_waitcnt vmcnt(2)
	ds_write_b128 v189, v[142:145]
	s_waitcnt vmcnt(1)
	ds_write_b128 v188, v[134:137]
	s_waitcnt vmcnt(0)
	ds_write_b128 v187, v[138:141]
	ds_read_b128 v[130:133], v171 offset:36928
	ds_read_b128 v[134:137], v170 offset:64
	ds_read_b128 v[138:141], v170 offset:4672
	ds_read_b128 v[142:145], v170 offset:9280
	ds_read_b128 v[146:149], v170 offset:13888
	s_waitcnt lgkmcnt(3)
	v_mfma_f32_32x32x16_bf16 v[114:129], v[130:133], v[134:137], v[114:129]
	s_waitcnt lgkmcnt(2)
	v_mfma_f32_32x32x16_bf16 v[82:97], v[130:133], v[138:141], v[82:97]
	s_waitcnt lgkmcnt(1)
	v_mfma_f32_32x32x16_bf16 v[50:65], v[130:133], v[142:145], v[50:65]
	s_waitcnt lgkmcnt(0)
	v_mfma_f32_32x32x16_bf16 v[18:33], v[130:133], v[146:149], v[18:33]
	ds_read_b128 v[130:133], v171 offset:41536
	s_waitcnt lgkmcnt(0)
	v_mfma_f32_32x32x16_bf16 v[98:113], v[130:133], v[134:137], v[98:113]
	v_mfma_f32_32x32x16_bf16 v[66:81], v[130:133], v[138:141], v[66:81]
	v_mfma_f32_32x32x16_bf16 v[34:49], v[130:133], v[142:145], v[34:49]
	v_mfma_f32_32x32x16_bf16 v[2:17], v[130:133], v[146:149], v[2:17]
	ds_read_b128 v[130:133], v171 offset:36960
	ds_read_b128 v[134:137], v170 offset:96
	ds_read_b128 v[138:141], v170 offset:4704
	ds_read_b128 v[142:145], v170 offset:9312
	ds_read_b128 v[146:149], v170 offset:13920
	v_add_u32_e32 v150, 0x12000, v170
	s_waitcnt lgkmcnt(3)
	v_mfma_f32_32x32x16_bf16 v[114:129], v[130:133], v[134:137], v[114:129]
	s_waitcnt lgkmcnt(2)
	v_mfma_f32_32x32x16_bf16 v[82:97], v[130:133], v[138:141], v[82:97]
	s_waitcnt lgkmcnt(1)
	v_mfma_f32_32x32x16_bf16 v[50:65], v[130:133], v[142:145], v[50:65]
	s_waitcnt lgkmcnt(0)
	v_mfma_f32_32x32x16_bf16 v[18:33], v[130:133], v[146:149], v[18:33]
	ds_read_b128 v[130:133], v171 offset:41568
	s_waitcnt lgkmcnt(0)
	s_barrier
	v_mfma_f32_32x32x16_bf16 v[98:113], v[130:133], v[134:137], v[98:113]
	ds_read_b128 v[134:137], v150
	v_mfma_f32_32x32x16_bf16 v[66:81], v[130:133], v[138:141], v[66:81]
	ds_read_b128 v[138:141], v150 offset:4608
	v_mfma_f32_32x32x16_bf16 v[34:49], v[130:133], v[142:145], v[34:49]
	ds_read_b128 v[142:145], v150 offset:9216
	v_mfma_f32_32x32x16_bf16 v[2:17], v[130:133], v[146:149], v[2:17]
	ds_read_b128 v[130:133], v191
	ds_read_b128 v[146:149], v150 offset:13824
	s_waitcnt lgkmcnt(1)
	v_mfma_f32_32x32x16_bf16 v[114:129], v[130:133], v[134:137], v[114:129]
	v_mfma_f32_32x32x16_bf16 v[82:97], v[130:133], v[138:141], v[82:97]
	v_mfma_f32_32x32x16_bf16 v[50:65], v[130:133], v[142:145], v[50:65]
	s_waitcnt lgkmcnt(0)
	v_mfma_f32_32x32x16_bf16 v[18:33], v[130:133], v[146:149], v[18:33]
	ds_read_b128 v[130:133], v191 offset:4608
	s_waitcnt lgkmcnt(0)
	v_mfma_f32_32x32x16_bf16 v[98:113], v[130:133], v[134:137], v[98:113]
	v_mfma_f32_32x32x16_bf16 v[66:81], v[130:133], v[138:141], v[66:81]
	v_mfma_f32_32x32x16_bf16 v[34:49], v[130:133], v[142:145], v[34:49]
	v_mfma_f32_32x32x16_bf16 v[2:17], v[130:133], v[146:149], v[2:17]
	ds_read_b128 v[130:133], v191 offset:32
	ds_read_b128 v[134:137], v150 offset:32
	ds_read_b128 v[138:141], v150 offset:4640
	ds_read_b128 v[142:145], v150 offset:9248
	ds_read_b128 v[146:149], v150 offset:13856
	s_waitcnt lgkmcnt(3)
	v_mfma_f32_32x32x16_bf16 v[114:129], v[130:133], v[134:137], v[114:129]
	s_waitcnt lgkmcnt(2)
	v_mfma_f32_32x32x16_bf16 v[82:97], v[130:133], v[138:141], v[82:97]
	s_waitcnt lgkmcnt(1)
	v_mfma_f32_32x32x16_bf16 v[50:65], v[130:133], v[142:145], v[50:65]
	s_waitcnt lgkmcnt(0)
	v_mfma_f32_32x32x16_bf16 v[18:33], v[130:133], v[146:149], v[18:33]
	ds_read_b128 v[130:133], v191 offset:4640
	s_waitcnt lgkmcnt(0)
	v_mfma_f32_32x32x16_bf16 v[98:113], v[130:133], v[134:137], v[98:113]
	v_mfma_f32_32x32x16_bf16 v[66:81], v[130:133], v[138:141], v[66:81]
	v_mfma_f32_32x32x16_bf16 v[34:49], v[130:133], v[142:145], v[34:49]
	v_mfma_f32_32x32x16_bf16 v[2:17], v[130:133], v[146:149], v[2:17]
	ds_read_b128 v[130:133], v191 offset:64
	ds_read_b128 v[134:137], v150 offset:64
	ds_read_b128 v[138:141], v150 offset:4672
	ds_read_b128 v[142:145], v150 offset:9280
	ds_read_b128 v[146:149], v150 offset:13888
	s_waitcnt lgkmcnt(3)
	v_mfma_f32_32x32x16_bf16 v[114:129], v[130:133], v[134:137], v[114:129]
	s_waitcnt lgkmcnt(2)
	v_mfma_f32_32x32x16_bf16 v[82:97], v[130:133], v[138:141], v[82:97]
	s_waitcnt lgkmcnt(1)
	v_mfma_f32_32x32x16_bf16 v[50:65], v[130:133], v[142:145], v[50:65]
	s_waitcnt lgkmcnt(0)
	v_mfma_f32_32x32x16_bf16 v[18:33], v[130:133], v[146:149], v[18:33]
	ds_read_b128 v[130:133], v191 offset:4672
	s_waitcnt lgkmcnt(0)
	v_mfma_f32_32x32x16_bf16 v[98:113], v[130:133], v[134:137], v[98:113]
	v_mfma_f32_32x32x16_bf16 v[66:81], v[130:133], v[138:141], v[66:81]
	v_mfma_f32_32x32x16_bf16 v[34:49], v[130:133], v[142:145], v[34:49]
	v_mfma_f32_32x32x16_bf16 v[2:17], v[130:133], v[146:149], v[2:17]
	ds_read_b128 v[130:133], v150 offset:96
	ds_read_b128 v[134:137], v150 offset:4704
	ds_read_b128 v[138:141], v150 offset:9312
	ds_read_b128 v[142:145], v150 offset:13920
	ds_read_b128 v[146:149], v191 offset:96
	ds_read_b128 v[150:153], v191 offset:4704
	s_waitcnt lgkmcnt(0)
	s_barrier
	v_mfma_f32_32x32x16_bf16 v[114:129], v[146:149], v[130:133], v[114:129]
	s_add_i32 s10, s10, s46
	s_cmp_ge_i32 s10, s1
	v_mfma_f32_32x32x16_bf16 v[82:97], v[146:149], v[134:137], v[82:97]
	v_mfma_f32_32x32x16_bf16 v[66:81], v[150:153], v[134:137], v[66:81]
	s_nop 7
	v_mul_f32_e32 v137, 0xbfb8aa3b, v114
	v_exp_f32_e32 v137, v137
	v_add_u32_e32 v136, s14, v182
	v_add_f32_e32 v137, 1.0, v137
	v_mfma_f32_32x32x16_bf16 v[50:65], v[146:149], v[138:141], v[50:65]
	v_mfma_f32_32x32x16_bf16 v[34:49], v[150:153], v[138:141], v[34:49]
	v_rcp_f32_e32 v138, v137
	v_mul_f32_e32 v137, 0xbfb8aa3b, v115
	v_exp_f32_e32 v137, v137
	s_nop 0
	v_add_f32_e32 v137, 1.0, v137
	v_mfma_f32_32x32x16_bf16 v[98:113], v[150:153], v[130:133], v[98:113]
	v_rcp_f32_e32 v139, v137
	v_or_b32_e32 v130, s15, v173
	v_ashrrev_i32_e32 v132, 1, v130
	v_ashrrev_i32_e32 v133, 31, v132
	v_pk_mul_f32 v[114:115], v[114:115], v[138:139]
	v_mov_b64_e32 v[130:131], s[40:41]
	v_mad_i64_i32 v[134:135], s[2:3], v136, s5, v[130:131]
	s_nop 4
	v_pk_mul_f32 v[114:115], v[98:99], v[114:115]
	v_mul_f32_e32 v98, 0xbfb8aa3b, v116
	v_mul_f32_e32 v99, 0xbfb8aa3b, v117
	v_exp_f32_e32 v98, v98
	v_exp_f32_e32 v99, v99
	v_cvt_pk_bf16_f32 v114, v114, v115
	v_mfma_f32_32x32x16_bf16 v[18:33], v[146:149], v[142:145], v[18:33]
	v_add_f32_e32 v98, 1.0, v98
	v_add_f32_e32 v99, 1.0, v99
	v_rcp_f32_e32 v98, v98
	v_rcp_f32_e32 v99, v99
	s_nop 0
	v_pk_mul_f32 v[98:99], v[116:117], v[98:99]
	s_nop 0
	v_pk_mul_f32 v[100:101], v[100:101], v[98:99]
	v_mul_f32_e32 v98, 0xbfb8aa3b, v118
	v_mul_f32_e32 v99, 0xbfb8aa3b, v119
	v_exp_f32_e32 v98, v98
	v_exp_f32_e32 v99, v99
	v_cvt_pk_bf16_f32 v115, v100, v101
	v_mfma_f32_32x32x16_bf16 v[2:17], v[150:153], v[142:145], v[2:17]
	v_add_f32_e32 v98, 1.0, v98
	v_add_f32_e32 v99, 1.0, v99
	v_rcp_f32_e32 v98, v98
	v_rcp_f32_e32 v99, v99
	s_nop 0
	v_pk_mul_f32 v[98:99], v[118:119], v[98:99]
	s_nop 0
	v_pk_mul_f32 v[102:103], v[102:103], v[98:99]
	v_mul_f32_e32 v98, 0xbfb8aa3b, v120
	v_cvt_pk_bf16_f32 v100, v102, v103
	v_mul_f32_e32 v102, 0xbfb8aa3b, v82
	v_mul_f32_e32 v103, 0xbfb8aa3b, v83
	v_exp_f32_e32 v102, v102
	v_exp_f32_e32 v103, v103
	v_mul_f32_e32 v99, 0xbfb8aa3b, v121
	v_exp_f32_e32 v98, v98
	v_add_f32_e32 v102, 1.0, v102
	v_add_f32_e32 v103, 1.0, v103
	v_rcp_f32_e32 v102, v102
	v_rcp_f32_e32 v103, v103
	v_exp_f32_e32 v99, v99
	v_add_f32_e32 v98, 1.0, v98
	v_rcp_f32_e32 v98, v98
	v_pk_mul_f32 v[82:83], v[82:83], v[102:103]
	v_add_f32_e32 v99, 1.0, v99
	v_pk_mul_f32 v[66:67], v[66:67], v[82:83]
	v_mul_f32_e32 v82, 0xbfb8aa3b, v84
	v_mul_f32_e32 v83, 0xbfb8aa3b, v85
	v_exp_f32_e32 v82, v82
	v_exp_f32_e32 v83, v83
	v_cvt_pk_bf16_f32 v66, v66, v67
	v_rcp_f32_e32 v99, v99
	v_add_f32_e32 v82, 1.0, v82
	v_add_f32_e32 v83, 1.0, v83
	v_rcp_f32_e32 v82, v82
	v_rcp_f32_e32 v83, v83
	v_pk_mul_f32 v[98:99], v[120:121], v[98:99]
	v_pk_mul_f32 v[82:83], v[84:85], v[82:83]
	s_nop 0
	v_pk_mul_f32 v[68:69], v[68:69], v[82:83]
	v_mul_f32_e32 v82, 0xbfb8aa3b, v86
	v_cvt_pk_bf16_f32 v67, v68, v69
	v_mul_f32_e32 v68, 0xbfb8aa3b, v50
	v_mul_f32_e32 v69, 0xbfb8aa3b, v51
	v_exp_f32_e32 v68, v68
	v_exp_f32_e32 v69, v69
	v_mul_f32_e32 v83, 0xbfb8aa3b, v87
	v_exp_f32_e32 v82, v82
	v_add_f32_e32 v68, 1.0, v68
	v_add_f32_e32 v69, 1.0, v69
	v_rcp_f32_e32 v68, v68
	v_rcp_f32_e32 v69, v69
	v_exp_f32_e32 v83, v83
	v_add_f32_e32 v82, 1.0, v82
	v_rcp_f32_e32 v82, v82
	v_pk_mul_f32 v[50:51], v[50:51], v[68:69]
	v_add_f32_e32 v83, 1.0, v83
	v_pk_mul_f32 v[34:35], v[34:35], v[50:51]
	v_mul_f32_e32 v50, 0xbfb8aa3b, v52
	v_mul_f32_e32 v51, 0xbfb8aa3b, v53
	v_exp_f32_e32 v50, v50
	v_exp_f32_e32 v51, v51
	v_cvt_pk_bf16_f32 v34, v34, v35
	v_rcp_f32_e32 v83, v83
	v_add_f32_e32 v50, 1.0, v50
	v_add_f32_e32 v51, 1.0, v51
	v_rcp_f32_e32 v50, v50
	v_rcp_f32_e32 v51, v51
	v_pk_mul_f32 v[82:83], v[86:87], v[82:83]
	v_pk_mul_f32 v[104:105], v[104:105], v[98:99]
	v_pk_mul_f32 v[70:71], v[70:71], v[82:83]
	v_pk_mul_f32 v[50:51], v[52:53], v[50:51]
	v_mul_f32_e32 v82, 0xbfb8aa3b, v88
	v_pk_mul_f32 v[36:37], v[36:37], v[50:51]
	v_mul_f32_e32 v50, 0xbfb8aa3b, v54
	v_cvt_pk_bf16_f32 v35, v36, v37
	v_mul_f32_e32 v36, 0xbfb8aa3b, v18
	v_mul_f32_e32 v37, 0xbfb8aa3b, v19
	v_exp_f32_e32 v36, v36
	v_exp_f32_e32 v37, v37
	v_mul_f32_e32 v51, 0xbfb8aa3b, v55
	v_exp_f32_e32 v50, v50
	v_add_f32_e32 v36, 1.0, v36
	v_add_f32_e32 v37, 1.0, v37
	v_rcp_f32_e32 v36, v36
	v_rcp_f32_e32 v37, v37
	v_exp_f32_e32 v51, v51
	v_mul_f32_e32 v83, 0xbfb8aa3b, v89
	v_exp_f32_e32 v82, v82
	v_pk_mul_f32 v[18:19], v[18:19], v[36:37]
	v_exp_f32_e32 v83, v83
	v_pk_mul_f32 v[2:3], v[2:3], v[18:19]
	v_mul_f32_e32 v18, 0xbfb8aa3b, v20
	v_mul_f32_e32 v19, 0xbfb8aa3b, v21
	v_exp_f32_e32 v18, v18
	v_exp_f32_e32 v19, v19
	v_add_f32_e32 v50, 1.0, v50
	v_add_f32_e32 v51, 1.0, v51
	v_add_f32_e32 v18, 1.0, v18
	v_add_f32_e32 v19, 1.0, v19
	v_rcp_f32_e32 v18, v18
	v_rcp_f32_e32 v19, v19
	v_rcp_f32_e32 v50, v50
	v_rcp_f32_e32 v51, v51
	v_mul_f32_e32 v98, 0xbfb8aa3b, v122
	v_pk_mul_f32 v[18:19], v[20:21], v[18:19]
	v_mul_f32_e32 v99, 0xbfb8aa3b, v123
	v_pk_mul_f32 v[4:5], v[4:5], v[18:19]
	v_mul_f32_e32 v18, 0xbfb8aa3b, v22
	v_mul_f32_e32 v19, 0xbfb8aa3b, v23
	v_exp_f32_e32 v18, v18
	v_exp_f32_e32 v19, v19
	v_exp_f32_e32 v98, v98
	v_exp_f32_e32 v99, v99
	v_add_f32_e32 v82, 1.0, v82
	v_add_f32_e32 v83, 1.0, v83
	v_rcp_f32_e32 v82, v82
	v_rcp_f32_e32 v83, v83
	v_pk_mul_f32 v[50:51], v[54:55], v[50:51]
	v_add_f32_e32 v18, 1.0, v18
	v_pk_mul_f32 v[38:39], v[38:39], v[50:51]
	v_mul_f32_e32 v50, 0xbfb8aa3b, v56
	v_mul_f32_e32 v51, 0xbfb8aa3b, v57
	v_exp_f32_e32 v50, v50
	v_exp_f32_e32 v51, v51
	v_add_f32_e32 v19, 1.0, v19
	v_add_f32_e32 v98, 1.0, v98
	v_add_f32_e32 v99, 1.0, v99
	v_rcp_f32_e32 v18, v18
	v_rcp_f32_e32 v19, v19
	v_rcp_f32_e32 v98, v98
	v_rcp_f32_e32 v99, v99
	v_pk_mul_f32 v[82:83], v[88:89], v[82:83]
	v_add_f32_e32 v50, 1.0, v50
	v_pk_mul_f32 v[72:73], v[72:73], v[82:83]
	v_mul_f32_e32 v82, 0xbfb8aa3b, v90
	v_mul_f32_e32 v83, 0xbfb8aa3b, v91
	v_exp_f32_e32 v82, v82
	v_exp_f32_e32 v83, v83
	v_add_f32_e32 v51, 1.0, v51
	v_rcp_f32_e32 v50, v50
	v_rcp_f32_e32 v51, v51
	v_pk_mul_f32 v[18:19], v[22:23], v[18:19]
	v_pk_mul_f32 v[98:99], v[122:123], v[98:99]
	v_pk_mul_f32 v[6:7], v[6:7], v[18:19]
	v_mul_f32_e32 v18, 0xbfb8aa3b, v24
	v_mul_f32_e32 v19, 0xbfb8aa3b, v25
	v_pk_mul_f32 v[106:107], v[106:107], v[98:99]
	v_mul_f32_e32 v98, 0xbfb8aa3b, v124
	v_mul_f32_e32 v99, 0xbfb8aa3b, v125
	v_exp_f32_e32 v18, v18
	v_exp_f32_e32 v19, v19
	v_exp_f32_e32 v98, v98
	v_exp_f32_e32 v99, v99
	v_add_f32_e32 v82, 1.0, v82
	v_add_f32_e32 v83, 1.0, v83
	v_rcp_f32_e32 v82, v82
	v_rcp_f32_e32 v83, v83
	v_pk_mul_f32 v[50:51], v[56:57], v[50:51]
	v_add_f32_e32 v18, 1.0, v18
	v_pk_mul_f32 v[40:41], v[40:41], v[50:51]
	v_mul_f32_e32 v50, 0xbfb8aa3b, v58
	v_mul_f32_e32 v51, 0xbfb8aa3b, v59
	v_exp_f32_e32 v50, v50
	v_exp_f32_e32 v51, v51
	v_add_f32_e32 v19, 1.0, v19
	v_add_f32_e32 v98, 1.0, v98
	v_add_f32_e32 v99, 1.0, v99
	v_rcp_f32_e32 v18, v18
	v_rcp_f32_e32 v19, v19
	v_rcp_f32_e32 v98, v98
	v_rcp_f32_e32 v99, v99
	v_pk_mul_f32 v[82:83], v[90:91], v[82:83]
	v_add_f32_e32 v50, 1.0, v50
	v_pk_mul_f32 v[74:75], v[74:75], v[82:83]
	v_mul_f32_e32 v82, 0xbfb8aa3b, v92
	v_mul_f32_e32 v83, 0xbfb8aa3b, v93
	v_exp_f32_e32 v82, v82
	v_exp_f32_e32 v83, v83
	v_add_f32_e32 v51, 1.0, v51
	v_rcp_f32_e32 v50, v50
	v_rcp_f32_e32 v51, v51
	v_pk_mul_f32 v[18:19], v[24:25], v[18:19]
	v_pk_mul_f32 v[98:99], v[124:125], v[98:99]
	v_pk_mul_f32 v[8:9], v[8:9], v[18:19]
	v_mul_f32_e32 v18, 0xbfb8aa3b, v26
	v_mul_f32_e32 v19, 0xbfb8aa3b, v27
	v_pk_mul_f32 v[108:109], v[108:109], v[98:99]
	v_mul_f32_e32 v98, 0xbfb8aa3b, v126
	v_mul_f32_e32 v99, 0xbfb8aa3b, v127
	v_exp_f32_e32 v18, v18
	v_exp_f32_e32 v19, v19
	v_exp_f32_e32 v98, v98
	v_exp_f32_e32 v99, v99
	v_add_f32_e32 v82, 1.0, v82
	v_add_f32_e32 v83, 1.0, v83
	v_rcp_f32_e32 v82, v82
	v_rcp_f32_e32 v83, v83
	v_pk_mul_f32 v[50:51], v[58:59], v[50:51]
	v_add_f32_e32 v18, 1.0, v18
	v_pk_mul_f32 v[42:43], v[42:43], v[50:51]
	v_mul_f32_e32 v50, 0xbfb8aa3b, v60
	v_mul_f32_e32 v51, 0xbfb8aa3b, v61
	v_exp_f32_e32 v50, v50
	v_exp_f32_e32 v51, v51
	v_add_f32_e32 v19, 1.0, v19
	v_add_f32_e32 v98, 1.0, v98
	v_add_f32_e32 v99, 1.0, v99
	v_rcp_f32_e32 v18, v18
	v_rcp_f32_e32 v19, v19
	v_rcp_f32_e32 v98, v98
	v_rcp_f32_e32 v99, v99
	v_pk_mul_f32 v[82:83], v[92:93], v[82:83]
	v_add_f32_e32 v50, 1.0, v50
	v_pk_mul_f32 v[76:77], v[76:77], v[82:83]
	v_mul_f32_e32 v82, 0xbfb8aa3b, v94
	v_mul_f32_e32 v83, 0xbfb8aa3b, v95
	v_exp_f32_e32 v82, v82
	v_exp_f32_e32 v83, v83
	v_add_f32_e32 v51, 1.0, v51
	v_rcp_f32_e32 v50, v50
	v_rcp_f32_e32 v51, v51
	v_pk_mul_f32 v[18:19], v[26:27], v[18:19]
	v_pk_mul_f32 v[98:99], v[126:127], v[98:99]
	v_pk_mul_f32 v[10:11], v[10:11], v[18:19]
	v_mul_f32_e32 v18, 0xbfb8aa3b, v28
	v_mul_f32_e32 v19, 0xbfb8aa3b, v29
	v_pk_mul_f32 v[110:111], v[110:111], v[98:99]
	v_mul_f32_e32 v98, 0xbfb8aa3b, v128
	v_mul_f32_e32 v99, 0xbfb8aa3b, v129
	v_exp_f32_e32 v18, v18
	v_exp_f32_e32 v19, v19
	v_exp_f32_e32 v98, v98
	v_exp_f32_e32 v99, v99
	v_add_f32_e32 v82, 1.0, v82
	v_add_f32_e32 v83, 1.0, v83
	v_rcp_f32_e32 v82, v82
	v_rcp_f32_e32 v83, v83
	v_pk_mul_f32 v[50:51], v[60:61], v[50:51]
	v_add_f32_e32 v18, 1.0, v18
	v_pk_mul_f32 v[44:45], v[44:45], v[50:51]
	v_mul_f32_e32 v50, 0xbfb8aa3b, v62
	v_mul_f32_e32 v51, 0xbfb8aa3b, v63
	v_exp_f32_e32 v50, v50
	v_exp_f32_e32 v51, v51
	v_add_f32_e32 v19, 1.0, v19
	v_add_f32_e32 v98, 1.0, v98
	v_add_f32_e32 v99, 1.0, v99
	v_rcp_f32_e32 v18, v18
	v_rcp_f32_e32 v19, v19
	v_rcp_f32_e32 v98, v98
	v_rcp_f32_e32 v99, v99
	v_pk_mul_f32 v[82:83], v[94:95], v[82:83]
	v_add_f32_e32 v50, 1.0, v50
	v_pk_mul_f32 v[78:79], v[78:79], v[82:83]
	v_mul_f32_e32 v82, 0xbfb8aa3b, v96
	v_mul_f32_e32 v83, 0xbfb8aa3b, v97
	v_exp_f32_e32 v82, v82
	v_exp_f32_e32 v83, v83
	v_add_f32_e32 v51, 1.0, v51
	v_rcp_f32_e32 v50, v50
	v_rcp_f32_e32 v51, v51
	v_pk_mul_f32 v[18:19], v[28:29], v[18:19]
	v_pk_mul_f32 v[98:99], v[128:129], v[98:99]
	v_pk_mul_f32 v[12:13], v[12:13], v[18:19]
	v_mul_f32_e32 v18, 0xbfb8aa3b, v30
	v_mul_f32_e32 v19, 0xbfb8aa3b, v31
	v_pk_mul_f32 v[112:113], v[112:113], v[98:99]
	v_lshlrev_b64 v[98:99], 1, v[132:133]
	v_exp_f32_e32 v18, v18
	v_exp_f32_e32 v19, v19
	v_lshl_add_u64 v[116:117], v[134:135], 0, v[98:99]
	v_add_f32_e32 v82, 1.0, v82
	v_add_f32_e32 v83, 1.0, v83
	v_lshl_add_u64 v[116:117], v[116:117], 0, v[0:1]
	v_cvt_pk_bf16_f32 v101, v104, v105
	v_rcp_f32_e32 v82, v82
	v_rcp_f32_e32 v83, v83
	v_pk_mul_f32 v[50:51], v[62:63], v[50:51]
	global_store_dwordx2 v[116:117], v[100:101], off offset:16
	v_cvt_pk_bf16_f32 v100, v106, v107
	v_cvt_pk_bf16_f32 v101, v108, v109
	v_pk_mul_f32 v[46:47], v[46:47], v[50:51]
	v_mul_f32_e32 v50, 0xbfb8aa3b, v64
	v_mul_f32_e32 v51, 0xbfb8aa3b, v65
	global_store_dwordx2 v[116:117], v[100:101], off offset:32
	v_cvt_pk_bf16_f32 v100, v110, v111
	v_cvt_pk_bf16_f32 v101, v112, v113
	v_exp_f32_e32 v50, v50
	v_exp_f32_e32 v51, v51
	v_add_f32_e32 v18, 1.0, v18
	v_add_f32_e32 v19, 1.0, v19
	global_store_dwordx2 v[116:117], v[100:101], off offset:48
	v_or_b32_e32 v100, 32, v136
	v_rcp_f32_e32 v18, v18
	v_rcp_f32_e32 v19, v19
	v_mad_i64_i32 v[100:101], s[2:3], v100, s5, v[130:131]
	v_pk_mul_f32 v[82:83], v[96:97], v[82:83]
	v_add_f32_e32 v50, 1.0, v50
	v_pk_mul_f32 v[80:81], v[80:81], v[82:83]
	v_lshl_add_u64 v[82:83], v[100:101], 0, v[98:99]
	v_lshl_add_u64 v[82:83], v[82:83], 0, v[0:1]
	v_add_f32_e32 v51, 1.0, v51
	global_store_dwordx2 v[82:83], v[66:67], off
	v_cvt_pk_bf16_f32 v66, v70, v71
	v_cvt_pk_bf16_f32 v67, v72, v73
	v_rcp_f32_e32 v50, v50
	v_rcp_f32_e32 v51, v51
	v_pk_mul_f32 v[18:19], v[30:31], v[18:19]
	global_store_dwordx2 v[82:83], v[66:67], off offset:16
	v_cvt_pk_bf16_f32 v66, v74, v75
	v_cvt_pk_bf16_f32 v67, v76, v77
	v_pk_mul_f32 v[14:15], v[14:15], v[18:19]
	v_mul_f32_e32 v18, 0xbfb8aa3b, v32
	v_mul_f32_e32 v19, 0xbfb8aa3b, v33
	global_store_dwordx2 v[82:83], v[66:67], off offset:32
	v_cvt_pk_bf16_f32 v66, v78, v79
	v_cvt_pk_bf16_f32 v67, v80, v81
	v_exp_f32_e32 v18, v18
	v_exp_f32_e32 v19, v19
	global_store_dwordx2 v[82:83], v[66:67], off offset:48
	v_or_b32_e32 v66, 64, v136
	v_mad_i64_i32 v[66:67], s[2:3], v66, s5, v[130:131]
	v_pk_mul_f32 v[50:51], v[64:65], v[50:51]
	v_add_f32_e32 v18, 1.0, v18
	v_pk_mul_f32 v[48:49], v[48:49], v[50:51]
	v_lshl_add_u64 v[50:51], v[66:67], 0, v[98:99]
	v_lshl_add_u64 v[50:51], v[50:51], 0, v[0:1]
	v_add_f32_e32 v19, 1.0, v19
	global_store_dwordx2 v[50:51], v[34:35], off
	v_cvt_pk_bf16_f32 v34, v38, v39
	v_cvt_pk_bf16_f32 v35, v40, v41
	v_rcp_f32_e32 v18, v18
	v_rcp_f32_e32 v19, v19
	global_store_dwordx2 v[50:51], v[34:35], off offset:16
	v_cvt_pk_bf16_f32 v34, v42, v43
	v_cvt_pk_bf16_f32 v35, v44, v45
	global_store_dwordx2 v[50:51], v[34:35], off offset:32
	v_cvt_pk_bf16_f32 v34, v46, v47
	v_cvt_pk_bf16_f32 v35, v48, v49
	global_store_dwordx2 v[50:51], v[34:35], off offset:48
	v_or_b32_e32 v34, 0x60, v136
	v_mad_i64_i32 v[34:35], s[2:3], v34, s5, v[130:131]
	v_pk_mul_f32 v[18:19], v[32:33], v[18:19]
	v_cvt_pk_bf16_f32 v2, v2, v3
	v_pk_mul_f32 v[16:17], v[16:17], v[18:19]
	v_lshl_add_u64 v[18:19], v[34:35], 0, v[98:99]
	v_lshl_add_u64 v[18:19], v[18:19], 0, v[0:1]
	v_cvt_pk_bf16_f32 v3, v4, v5
	global_store_dwordx2 v[18:19], v[2:3], off
	v_cvt_pk_bf16_f32 v2, v6, v7
	v_cvt_pk_bf16_f32 v3, v8, v9
	global_store_dwordx2 v[18:19], v[2:3], off offset:16
	v_cvt_pk_bf16_f32 v2, v10, v11
	v_cvt_pk_bf16_f32 v3, v12, v13
	global_store_dwordx2 v[18:19], v[2:3], off offset:32
	v_cvt_pk_bf16_f32 v2, v14, v15
	v_cvt_pk_bf16_f32 v3, v16, v17
	global_store_dwordx2 v[116:117], v[114:115], off
	global_store_dwordx2 v[18:19], v[2:3], off offset:48
	s_cbranch_scc0 .LBB0_53

.LBB0_159:
	s_or_b64 exec, exec, s[14:15]
	global_load_dwordx4 v[124:127], v[10:11], off offset:128
	s_movk_i32 s6, 0xd0
	v_mul_lo_u32 v9, v12, s6
	v_lshl_add_u32 v157, v6, 4, v9
	v_mul_lo_u32 v6, v7, s6
	v_lshl_add_u32 v158, v8, 4, v6
	s_waitcnt vmcnt(3)
	ds_write_b128 v157, v[104:107]
	s_and_saveexec_b64 s[12:13], s[38:39]
	ds_write_b128 v158, v[112:115]
	s_or_b64 exec, exec, s[12:13]
	v_mad_i64_i32 v[6:7], s[12:13], v156, s54, 0
	s_and_b64 s[12:13], s[88:89], exec
	s_cselect_b32 s14, 0x84, 4
	v_lshl_add_u64 v[6:7], s[2:3], 0, v[6:7]
	s_add_u32 s2, s52, s96
	v_lshl_add_u64 v[6:7], v[6:7], 0, v[0:1]
	s_addc_u32 s3, s53, 0
	v_lshl_add_u64 v[150:151], s[2:3], 0, v[6:7]
	s_add_u32 s2, s40, s41
	v_and_b32_e32 v8, 31, v148
	s_addc_u32 s3, s23, 0
	v_mul_u32_u24_e32 v16, 0xd0, v8
	v_lshlrev_b32_e32 v8, 6, v8
	v_cmp_lt_i32_e32 vcc, v207, v206
	s_add_u32 s2, s52, s2
	v_mul_lo_u32 v9, v156, s4
	v_sub_u32_e32 v17, v16, v8
	v_cndmask_b32_e32 v8, v205, v207, vcc
	s_addc_u32 s3, s53, s3
	v_mov_b32_e32 v14, v1
	v_mov_b32_e32 v15, v1
	v_lshl_add_u32 v160, v140, 4, v9
	v_lshlrev_b32_e32 v159, 2, v8
	v_lshl_add_u64 v[152:153], v[2:3], 1, s[2:3]
	v_lshl_add_u64 v[154:155], v[4:5], 1, s[2:3]
	v_mov_b32_e32 v0, v1
	v_mov_b32_e32 v2, v1
	v_mov_b32_e32 v3, v1
	v_mov_b32_e32 v4, v1
	v_mov_b32_e32 v5, v1
	v_mov_b32_e32 v6, v1
	v_mov_b32_e32 v7, v1
	v_mov_b32_e32 v8, v1
	v_mov_b32_e32 v9, v1
	v_mov_b32_e32 v10, v1
	v_mov_b32_e32 v11, v1
	v_mov_b32_e32 v12, v1
	v_mov_b32_e32 v13, v1
	v_add_u32_e32 v164, v16, v130
	v_add_u32_e32 v165, v17, v130
	v_mov_b64_e32 v[30:31], v[14:15]
	v_mov_b64_e32 v[46:47], v[14:15]
	s_mov_b32 s22, 0
	v_mov_b32_e32 v161, 0
	v_bfrev_b32_e32 v218, 1
	v_mov_b32_e32 v219, v218
	v_mov_b32_e32 v220, v218
	v_mov_b32_e32 v221, v218
	v_mov_b32_e32 v222, v218
	v_mov_b32_e32 v223, v218
	v_mov_b32_e32 v224, v218
	v_mov_b32_e32 v225, v218
	v_mov_b32_e32 v226, v218
	v_mov_b32_e32 v227, v218
	v_mov_b32_e32 v228, v218
	v_mov_b32_e32 v229, v218
	v_mov_b32_e32 v230, v218
	v_mov_b32_e32 v231, v218
	v_mov_b32_e32 v232, v218
	v_mov_b32_e32 v233, v218
	v_mov_b64_e32 v[28:29], v[12:13]
	v_mov_b64_e32 v[26:27], v[10:11]
	v_mov_b64_e32 v[24:25], v[8:9]
	v_mov_b64_e32 v[22:23], v[6:7]
	v_mov_b64_e32 v[20:21], v[4:5]
	v_mov_b64_e32 v[18:19], v[2:3]
	v_mov_b64_e32 v[16:17], v[0:1]
	v_mov_b64_e32 v[44:45], v[12:13]
	v_mov_b64_e32 v[42:43], v[10:11]
	v_mov_b64_e32 v[40:41], v[8:9]
	v_mov_b64_e32 v[38:39], v[6:7]
	v_mov_b64_e32 v[36:37], v[4:5]
	v_mov_b64_e32 v[34:35], v[2:3]
	v_mov_b64_e32 v[32:33], v[0:1]
	v_mov_b32_e32 v0, 0
	s_waitcnt vmcnt(2)
	ds_write_b128 v160, v[120:123] offset:13312
	s_waitcnt lgkmcnt(0)
	s_barrier

.LBB0_166:
	ds_read_b128 v[2:5], v164
	ds_read_b128 v[6:9], v164 offset:32
	ds_read_b128 v[10:13], v164 offset:6656
	ds_read_b128 v[128:131], v164 offset:6688
	ds_read_b128 v[132:135], v164 offset:64
	ds_read_b128 v[136:139], v164 offset:96
	ds_read_b128 v[140:143], v164 offset:6720
	ds_read_b128 v[144:147], v164 offset:6752
	ds_read_b128 v[166:169], v164 offset:128
	ds_read_b128 v[170:173], v164 offset:160
	ds_read_b128 v[174:177], v164 offset:6784
	ds_read_b128 v[178:181], v164 offset:6816
	s_cmp_eq_u32 s22, 0
	s_cselect_b64 s[40:41], -1, 0
	s_waitcnt lgkmcnt(11)
	s_nop 0
	v_mfma_f32_32x32x16_bf16 v[64:79], v[2:5], v[80:83], v[218:233]
	s_waitcnt lgkmcnt(9)
	v_mfma_f32_32x32x16_bf16 v[48:63], v[10:13], v[80:83], v[218:233]
	v_mfma_f32_32x32x16_bf16 v[64:79], v[6:9], v[84:87], v[64:79]
	s_waitcnt lgkmcnt(8)
	v_mfma_f32_32x32x16_bf16 v[48:63], v[128:131], v[84:87], v[48:63]
	s_waitcnt lgkmcnt(7)
	v_mfma_f32_32x32x16_bf16 v[64:79], v[132:135], v[88:91], v[64:79]
	s_waitcnt lgkmcnt(5)
	v_mfma_f32_32x32x16_bf16 v[48:63], v[140:143], v[88:91], v[48:63]
	v_mfma_f32_32x32x16_bf16 v[64:79], v[136:139], v[92:95], v[64:79]
	s_waitcnt lgkmcnt(4)
	v_mfma_f32_32x32x16_bf16 v[48:63], v[144:147], v[92:95], v[48:63]
	ds_read_b128 v[144:147], v165 offset:13312
	ds_read_b128 v[140:143], v165 offset:13344
	ds_read_b128 v[136:139], v165 offset:13376
	ds_read_b128 v[132:135], v165 offset:13408
	ds_read_b128 v[128:131], v165 offset:17920
	ds_read_b128 v[10:13], v165 offset:17952
	ds_read_b128 v[2:5], v165 offset:17984
	ds_read_b128 v[6:9], v165 offset:18016
	s_waitcnt lgkmcnt(11)
	v_mfma_f32_32x32x16_bf16 v[64:79], v[166:169], v[96:99], v[64:79]
	s_waitcnt lgkmcnt(9)
	v_mfma_f32_32x32x16_bf16 v[48:63], v[174:177], v[96:99], v[48:63]
	v_mfma_f32_32x32x16_bf16 v[64:79], v[170:173], v[100:103], v[64:79]
	s_waitcnt lgkmcnt(8)
	v_mfma_f32_32x32x16_bf16 v[48:63], v[178:181], v[100:103], v[48:63]
	s_nop 9
	v_max_i32_e32 v166, v64, v65
	s_nop 0
	v_max3_i32 v166, v166, v48, v49
	v_max3_i32 v166, v166, v66, v67
	v_max3_i32 v166, v166, v50, v51
	v_max3_i32 v166, v166, v68, v69
	v_max3_i32 v166, v166, v52, v53
	v_max3_i32 v166, v166, v70, v71
	v_max3_i32 v166, v166, v54, v55
	v_max3_i32 v166, v166, v72, v73
	v_max3_i32 v166, v166, v56, v57
	v_max3_i32 v166, v166, v74, v75
	v_max3_i32 v166, v166, v58, v59
	v_max3_i32 v166, v166, v76, v77
	v_max3_i32 v166, v166, v60, v61
	v_max3_i32 v166, v166, v78, v79
	v_max3_i32 v166, v166, v62, v63
	v_cmp_lt_i32_e32 vcc, s74, v166
	s_or_b64 vcc, s[40:41], vcc
	s_cbranch_vccz .LBB0_168
	v_max_f32_e32 v166, v49, v49
	v_max_f32_e32 v167, v65, v65
	v_max_f32_e32 v166, v167, v166
	v_max_f32_e32 v167, v50, v50
	v_max_f32_e32 v168, v66, v66
	v_max_f32_e32 v167, v168, v167
	v_max_f32_e32 v168, v51, v51
	v_max_f32_e32 v169, v67, v67
	v_max3_f32 v166, v64, v48, v166
	v_max_f32_e32 v168, v169, v168
	v_max3_f32 v166, v166, v167, v168
	v_max_f32_e32 v167, v52, v52
	v_max_f32_e32 v168, v68, v68
	v_max_f32_e32 v167, v168, v167
	v_max_f32_e32 v168, v53, v53
	v_max_f32_e32 v169, v69, v69
	v_max_f32_e32 v168, v169, v168
	v_max3_f32 v166, v166, v167, v168
	v_max_f32_e32 v167, v54, v54
	v_max_f32_e32 v168, v70, v70
	v_max_f32_e32 v167, v168, v167
	v_max_f32_e32 v168, v55, v55
	v_max_f32_e32 v169, v71, v71
	v_max_f32_e32 v168, v169, v168
	v_max3_f32 v166, v166, v167, v168
	v_max_f32_e32 v167, v56, v56
	v_max_f32_e32 v168, v72, v72
	v_max_f32_e32 v167, v168, v167
	v_max_f32_e32 v168, v57, v57
	v_max_f32_e32 v169, v73, v73
	v_max_f32_e32 v168, v169, v168
	v_max3_f32 v166, v166, v167, v168
	v_max_f32_e32 v167, v58, v58
	v_max_f32_e32 v168, v74, v74
	v_max_f32_e32 v167, v168, v167
	v_max_f32_e32 v168, v59, v59
	v_max_f32_e32 v169, v75, v75
	v_max_f32_e32 v168, v169, v168
	v_max3_f32 v166, v166, v167, v168
	v_max_f32_e32 v167, v60, v60
	v_max_f32_e32 v168, v76, v76
	v_max_f32_e32 v167, v168, v167
	v_max_f32_e32 v168, v61, v61
	v_max_f32_e32 v169, v77, v77
	v_max_f32_e32 v168, v169, v168
	v_max3_f32 v166, v166, v167, v168
	v_max_f32_e32 v167, v62, v62
	v_max_f32_e32 v168, v78, v78
	v_max_f32_e32 v167, v168, v167
	v_max_f32_e32 v168, v63, v63
	v_max_f32_e32 v169, v79, v79
	v_max_f32_e32 v168, v169, v168
	v_max3_f32 v166, v166, v167, v168
	ds_bpermute_b32 v167, v159, v166
	v_mov_b32_e32 v168, v64
	v_mov_b32_e32 v64, v65
	v_mov_b32_e32 v65, v66
	v_mov_b32_e32 v66, v67
	s_waitcnt lgkmcnt(0)
	v_max_f32_e32 v167, v167, v167
	v_max_f32_e32 v166, v166, v167
	v_max_f32_e32 v167, 0, v166
	v_cndmask_b32_e64 v166, v167, v166, s[40:41]
	v_exp_f32_e64 v167, -v166
	v_mov_b32_e32 v67, v68
	v_mov_b32_e32 v169, v48
	v_add_f32_e32 v161, v161, v166
	v_xor_b32_e32 v218, 0x80000000, v161
	v_mov_b32_e32 v219, v218
	v_mov_b32_e32 v220, v218
	v_mov_b32_e32 v221, v218
	v_mov_b32_e32 v222, v218
	v_mov_b32_e32 v223, v218
	v_mov_b32_e32 v224, v218
	v_mov_b32_e32 v225, v218
	v_mov_b32_e32 v226, v218
	v_mov_b32_e32 v227, v218
	v_mov_b32_e32 v228, v218
	v_mov_b32_e32 v229, v218
	v_mov_b32_e32 v230, v218
	v_mov_b32_e32 v231, v218
	v_mov_b32_e32 v232, v218
	v_mov_b32_e32 v233, v218
	v_pk_add_f32 v[170:171], v[64:65], v[166:167] op_sel_hi:[1,0] neg_lo:[0,1] neg_hi:[0,1]
	v_mov_b32_e32 v65, v50
	v_mov_b32_e32 v50, v51
	v_mov_b32_e32 v51, v52
	v_pk_add_f32 v[172:173], v[66:67], v[166:167] op_sel_hi:[1,0] neg_lo:[0,1] neg_hi:[0,1]
	v_pk_add_f32 v[66:67], v[50:51], v[166:167] op_sel_hi:[1,0] neg_lo:[0,1] neg_hi:[0,1]
	v_mov_b32_e32 v50, v69
	v_mov_b32_e32 v51, v70
	v_pk_add_f32 v[174:175], v[50:51], v[166:167] op_sel_hi:[1,0] neg_lo:[0,1] neg_hi:[0,1]
	v_mov_b32_e32 v50, v53
	v_mov_b32_e32 v51, v54
	v_pk_add_f32 v[68:69], v[50:51], v[166:167] op_sel_hi:[1,0] neg_lo:[0,1] neg_hi:[0,1]
	v_mov_b32_e32 v50, v71
	v_mov_b32_e32 v51, v72
	v_pk_add_f32 v[176:177], v[50:51], v[166:167] op_sel_hi:[1,0] neg_lo:[0,1] neg_hi:[0,1]
	v_mov_b32_e32 v50, v55
	v_mov_b32_e32 v51, v56
	v_pk_add_f32 v[70:71], v[50:51], v[166:167] op_sel_hi:[1,0] neg_lo:[0,1] neg_hi:[0,1]
	v_mov_b32_e32 v50, v73
	v_mov_b32_e32 v51, v74
	v_pk_add_f32 v[178:179], v[50:51], v[166:167] op_sel_hi:[1,0] neg_lo:[0,1] neg_hi:[0,1]
	v_mov_b32_e32 v50, v57
	v_mov_b32_e32 v51, v58
	v_pk_add_f32 v[72:73], v[50:51], v[166:167] op_sel_hi:[1,0] neg_lo:[0,1] neg_hi:[0,1]
	v_mov_b32_e32 v50, v75
	v_mov_b32_e32 v51, v76
	v_pk_add_f32 v[180:181], v[50:51], v[166:167] op_sel_hi:[1,0] neg_lo:[0,1] neg_hi:[0,1]
	v_mov_b32_e32 v50, v59
	v_mov_b32_e32 v51, v60
	v_pk_add_f32 v[74:75], v[50:51], v[166:167] op_sel_hi:[1,0] neg_lo:[0,1] neg_hi:[0,1]
	v_mov_b32_e32 v50, v77
	v_mov_b32_e32 v51, v78
	v_mov_b32_e32 v64, v49
	v_pk_add_f32 v[182:183], v[50:51], v[166:167] op_sel_hi:[1,0] neg_lo:[0,1] neg_hi:[0,1]
	v_mov_b32_e32 v50, v61
	v_mov_b32_e32 v51, v62
	v_cndmask_b32_e64 v48, v167, 1.0, s[40:41]
	v_pk_add_f32 v[168:169], v[168:169], v[166:167] op_sel_hi:[1,0] neg_lo:[0,1] neg_hi:[0,1]
	v_pk_add_f32 v[64:65], v[64:65], v[166:167] op_sel_hi:[1,0] neg_lo:[0,1] neg_hi:[0,1]
	v_pk_add_f32 v[76:77], v[50:51], v[166:167] op_sel_hi:[1,0] neg_lo:[0,1] neg_hi:[0,1]
	v_mul_f32_e32 v0, v0, v48
	v_pk_mul_f32 v[46:47], v[46:47], v[48:49] op_sel_hi:[1,0]
	v_pk_mul_f32 v[44:45], v[44:45], v[48:49] op_sel_hi:[1,0]
	v_pk_mul_f32 v[42:43], v[42:43], v[48:49] op_sel_hi:[1,0]
	v_pk_mul_f32 v[40:41], v[40:41], v[48:49] op_sel_hi:[1,0]
	v_pk_mul_f32 v[38:39], v[38:39], v[48:49] op_sel_hi:[1,0]
	v_pk_mul_f32 v[36:37], v[36:37], v[48:49] op_sel_hi:[1,0]
	v_pk_mul_f32 v[34:35], v[34:35], v[48:49] op_sel_hi:[1,0]
	v_pk_mul_f32 v[32:33], v[32:33], v[48:49] op_sel_hi:[1,0]
	v_pk_mul_f32 v[30:31], v[30:31], v[48:49] op_sel_hi:[1,0]
	v_pk_mul_f32 v[28:29], v[28:29], v[48:49] op_sel_hi:[1,0]
	v_pk_mul_f32 v[26:27], v[26:27], v[48:49] op_sel_hi:[1,0]
	v_pk_mul_f32 v[24:25], v[24:25], v[48:49] op_sel_hi:[1,0]
	v_pk_mul_f32 v[22:23], v[22:23], v[48:49] op_sel_hi:[1,0]
	v_pk_mul_f32 v[20:21], v[20:21], v[48:49] op_sel_hi:[1,0]
	v_pk_mul_f32 v[18:19], v[18:19], v[48:49] op_sel_hi:[1,0]
	v_pk_mul_f32 v[16:17], v[16:17], v[48:49] op_sel_hi:[1,0]
	v_sub_f32_e32 v79, v79, v166
	v_sub_f32_e32 v63, v63, v166
	v_mov_b32_e32 v49, v64
	v_mov_b32_e32 v50, v65
	v_mov_b32_e32 v51, v66
	v_mov_b32_e32 v52, v67
	v_mov_b32_e32 v53, v68
	v_mov_b32_e32 v54, v69
	v_mov_b32_e32 v55, v70
	v_mov_b32_e32 v56, v71
	v_mov_b32_e32 v57, v72
	v_mov_b32_e32 v58, v73
	v_mov_b32_e32 v59, v74
	v_mov_b32_e32 v60, v75
	v_mov_b32_e32 v61, v76
	v_mov_b32_e32 v62, v77
	v_mov_b32_e32 v65, v170
	v_mov_b32_e32 v66, v171
	v_mov_b32_e32 v67, v172
	v_mov_b32_e32 v68, v173
	v_mov_b32_e32 v69, v174
	v_mov_b32_e32 v70, v175
	v_mov_b32_e32 v71, v176
	v_mov_b32_e32 v72, v177
	v_mov_b32_e32 v73, v178
	v_mov_b32_e32 v74, v179
	v_mov_b32_e32 v75, v180
	v_mov_b32_e32 v76, v181
	v_mov_b32_e32 v77, v182
	v_mov_b32_e32 v78, v183
	v_mov_b32_e32 v64, v168
	v_mov_b32_e32 v48, v169
.LBB0_168:
	v_exp_f32_e32 v64, v64
	v_exp_f32_e32 v65, v65
	v_exp_f32_e32 v66, v66
	v_exp_f32_e32 v67, v67
	v_exp_f32_e32 v68, v68
	v_exp_f32_e32 v69, v69
	v_exp_f32_e32 v70, v70
	v_exp_f32_e32 v71, v71
	v_cvt_pk_bf16_f32 v166, v64, v65
	v_cvt_pk_bf16_f32 v167, v66, v67
	v_cvt_pk_bf16_f32 v168, v68, v69
	v_cvt_pk_bf16_f32 v169, v70, v71
	v_exp_f32_e32 v72, v72
	v_exp_f32_e32 v73, v73
	s_waitcnt lgkmcnt(0)
	v_mfma_f32_32x32x16_bf16 v[32:47], v[144:147], v[166:169], v[32:47]
	v_exp_f32_e32 v74, v74
	v_exp_f32_e32 v75, v75
	v_exp_f32_e32 v76, v76
	v_exp_f32_e32 v77, v77
	v_exp_f32_e32 v78, v78
	v_exp_f32_e32 v79, v79
	v_cvt_pk_bf16_f32 v170, v72, v73
	v_mfma_f32_32x32x16_bf16 v[16:31], v[128:131], v[166:169], v[16:31]
	v_cvt_pk_bf16_f32 v171, v74, v75
	v_cvt_pk_bf16_f32 v172, v76, v77
	v_cvt_pk_bf16_f32 v173, v78, v79
	v_exp_f32_e32 v48, v48
	v_exp_f32_e32 v49, v49
	v_exp_f32_e32 v50, v50
	v_exp_f32_e32 v51, v51
	v_mfma_f32_32x32x16_bf16 v[32:47], v[140:143], v[170:173], v[32:47]
	v_exp_f32_e32 v52, v52
	v_exp_f32_e32 v53, v53
	v_exp_f32_e32 v54, v54
	v_exp_f32_e32 v55, v55
	v_cvt_pk_bf16_f32 v174, v48, v49
	v_cvt_pk_bf16_f32 v175, v50, v51
	v_cvt_pk_bf16_f32 v176, v52, v53
	v_mfma_f32_32x32x16_bf16 v[16:31], v[10:13], v[170:173], v[16:31]
	v_cvt_pk_bf16_f32 v177, v54, v55
	v_exp_f32_e32 v56, v56
	v_exp_f32_e32 v57, v57
	v_exp_f32_e32 v58, v58
	v_exp_f32_e32 v59, v59
	v_exp_f32_e32 v60, v60
	v_exp_f32_e32 v61, v61
	v_mfma_f32_32x32x16_bf16 v[32:47], v[136:139], v[174:177], v[32:47]
	v_exp_f32_e32 v62, v62
	v_exp_f32_e32 v63, v63
	v_cvt_pk_bf16_f32 v178, v56, v57
	v_cvt_pk_bf16_f32 v179, v58, v59
	v_cvt_pk_bf16_f32 v180, v60, v61
	v_cvt_pk_bf16_f32 v181, v62, v63
	s_waitcnt vmcnt(1)
	ds_write_b128 v157, v[116:119] offset:22528
	v_mfma_f32_32x32x16_bf16 v[16:31], v[2:5], v[174:177], v[16:31]
	v_mfma_f32_32x32x16_bf16 v[32:47], v[132:135], v[178:181], v[32:47]
	v_mfma_f32_32x32x16_bf16 v[16:31], v[6:9], v[178:181], v[16:31]
	s_and_saveexec_b64 s[12:13], s[38:39]
	ds_write_b128 v158, v[108:111] offset:22528
	s_or_b64 exec, exec, s[12:13]
	s_add_i32 s12, s22, 3
	s_cmp_ge_u32 s12, s14
	s_waitcnt vmcnt(0)
	ds_write_b128 v160, v[124:127] offset:35840
	s_waitcnt lgkmcnt(0)
	s_barrier
	s_cbranch_scc1 .LBB0_174
	v_add_co_u32_e32 v2, vcc, 0x9186000, v14
	s_nop 1
	v_addc_co_u32_e32 v3, vcc, 0, v15, vcc
	global_load_dwordx4 v[116:119], v[2:3], off offset:2048
	s_and_saveexec_b64 s[12:13], s[38:39]
	s_cbranch_execz .LBB0_173
	v_lshl_add_u64 v[2:3], v[154:155], 0, s[20:21]
	v_add_co_u32_e32 v2, vcc, 0x9186000, v2
	s_nop 1
	v_addc_co_u32_e32 v3, vcc, 0, v3, vcc
	global_load_dwordx4 v[108:111], v[2:3], off offset:2048

.LBB0_174:
	v_add_f32_e32 v2, 0, v64
	v_add_f32_e32 v3, 0, v48
	v_add_f32_e32 v2, v2, v65
	v_add_f32_e32 v3, v3, v49
	v_add_f32_e32 v2, v66, v2
	v_add_f32_e32 v3, v50, v3
	v_add_f32_e32 v2, v67, v2
	v_add_f32_e32 v3, v51, v3
	v_add_f32_e32 v2, v68, v2
	v_add_f32_e32 v3, v52, v3
	v_add_f32_e32 v2, v69, v2
	v_add_f32_e32 v3, v53, v3
	v_add_f32_e32 v2, v70, v2
	v_add_f32_e32 v3, v54, v3
	v_add_f32_e32 v2, v71, v2
	v_add_f32_e32 v3, v55, v3
	v_add_f32_e32 v2, v72, v2
	v_add_f32_e32 v3, v56, v3
	v_add_f32_e32 v2, v73, v2
	v_add_f32_e32 v3, v57, v3
	v_add_f32_e32 v2, v74, v2
	v_add_f32_e32 v3, v58, v3
	v_add_f32_e32 v2, v75, v2
	v_add_f32_e32 v3, v59, v3
	v_add_f32_e32 v2, v76, v2
	v_add_f32_e32 v3, v60, v3
	v_add_f32_e32 v2, v77, v2
	v_add_f32_e32 v3, v61, v3
	v_add_f32_e32 v2, v78, v2
	v_add_f32_e32 v3, v62, v3
	v_add_f32_e32 v2, v79, v2
	v_add_f32_e32 v3, v63, v3
	v_add_f32_e32 v2, v3, v2
	v_add_f32_e32 v0, v0, v2
	ds_read_b128 v[2:5], v164 offset:22528
	ds_read_b128 v[6:9], v164 offset:22560
	ds_read_b128 v[10:13], v164 offset:29184
	ds_read_b128 v[128:131], v164 offset:29216
	ds_read_b128 v[132:135], v164 offset:22592
	ds_read_b128 v[136:139], v164 offset:22624
	ds_read_b128 v[140:143], v164 offset:29248
	ds_read_b128 v[144:147], v164 offset:29280
	ds_read_b128 v[166:169], v164 offset:22656
	ds_read_b128 v[170:173], v164 offset:22688
	ds_read_b128 v[174:177], v164 offset:29312
	ds_read_b128 v[178:181], v164 offset:29344
	s_waitcnt lgkmcnt(11)
	s_nop 0
	v_mfma_f32_32x32x16_bf16 v[64:79], v[2:5], v[80:83], v[218:233]
	s_waitcnt lgkmcnt(9)
	v_mfma_f32_32x32x16_bf16 v[48:63], v[10:13], v[80:83], v[218:233]
	v_mfma_f32_32x32x16_bf16 v[64:79], v[6:9], v[84:87], v[64:79]
	s_waitcnt lgkmcnt(8)
	v_mfma_f32_32x32x16_bf16 v[48:63], v[128:131], v[84:87], v[48:63]
	s_waitcnt lgkmcnt(7)
	v_mfma_f32_32x32x16_bf16 v[64:79], v[132:135], v[88:91], v[64:79]
	s_waitcnt lgkmcnt(5)
	v_mfma_f32_32x32x16_bf16 v[48:63], v[140:143], v[88:91], v[48:63]
	v_mfma_f32_32x32x16_bf16 v[64:79], v[136:139], v[92:95], v[64:79]
	s_waitcnt lgkmcnt(4)
	v_mfma_f32_32x32x16_bf16 v[48:63], v[144:147], v[92:95], v[48:63]
	ds_read_b128 v[144:147], v165 offset:35840
	ds_read_b128 v[140:143], v165 offset:35872
	ds_read_b128 v[136:139], v165 offset:35904
	ds_read_b128 v[132:135], v165 offset:35936
	ds_read_b128 v[128:131], v165 offset:40448
	ds_read_b128 v[10:13], v165 offset:40480
	ds_read_b128 v[2:5], v165 offset:40512
	ds_read_b128 v[6:9], v165 offset:40544
	s_waitcnt lgkmcnt(11)
	v_mfma_f32_32x32x16_bf16 v[64:79], v[166:169], v[96:99], v[64:79]
	s_waitcnt lgkmcnt(9)
	v_mfma_f32_32x32x16_bf16 v[48:63], v[174:177], v[96:99], v[48:63]
	v_mfma_f32_32x32x16_bf16 v[64:79], v[170:173], v[100:103], v[64:79]
	s_waitcnt lgkmcnt(8)
	v_mfma_f32_32x32x16_bf16 v[48:63], v[178:181], v[100:103], v[48:63]
	s_nop 9
	v_max_i32_e32 v14, v64, v65
	s_nop 0
	v_max3_i32 v14, v14, v48, v49
	v_max3_i32 v14, v14, v66, v67
	v_max3_i32 v14, v14, v50, v51
	v_max3_i32 v14, v14, v68, v69
	v_max3_i32 v14, v14, v52, v53
	v_max3_i32 v14, v14, v70, v71
	v_max3_i32 v14, v14, v54, v55
	v_max3_i32 v14, v14, v72, v73
	v_max3_i32 v14, v14, v56, v57
	v_max3_i32 v14, v14, v74, v75
	v_max3_i32 v14, v14, v58, v59
	v_max3_i32 v14, v14, v76, v77
	v_max3_i32 v14, v14, v60, v61
	v_max3_i32 v14, v14, v78, v79
	v_max3_i32 v14, v14, v62, v63
	v_cmp_lt_i32_e32 vcc, s74, v14
	s_cbranch_vccz .LBB0_176
	v_max_f32_e32 v14, v49, v49
	v_max_f32_e32 v15, v65, v65
	v_max_f32_e32 v14, v15, v14
	v_max_f32_e32 v15, v50, v50
	v_max_f32_e32 v166, v66, v66
	v_max_f32_e32 v15, v166, v15
	v_max_f32_e32 v166, v51, v51
	v_max_f32_e32 v167, v67, v67
	v_max3_f32 v14, v64, v48, v14
	v_max_f32_e32 v166, v167, v166
	v_max3_f32 v14, v14, v15, v166
	v_max_f32_e32 v15, v52, v52
	v_max_f32_e32 v166, v68, v68
	v_max_f32_e32 v15, v166, v15
	v_max_f32_e32 v166, v53, v53
	v_max_f32_e32 v167, v69, v69
	v_max_f32_e32 v166, v167, v166
	v_max3_f32 v14, v14, v15, v166
	v_max_f32_e32 v15, v54, v54
	v_max_f32_e32 v166, v70, v70
	v_max_f32_e32 v15, v166, v15
	v_max_f32_e32 v166, v55, v55
	v_max_f32_e32 v167, v71, v71
	v_max_f32_e32 v166, v167, v166
	v_max3_f32 v14, v14, v15, v166
	v_max_f32_e32 v15, v56, v56
	v_max_f32_e32 v166, v72, v72
	v_max_f32_e32 v15, v166, v15
	v_max_f32_e32 v166, v57, v57
	v_max_f32_e32 v167, v73, v73
	v_max_f32_e32 v166, v167, v166
	v_max3_f32 v14, v14, v15, v166
	v_max_f32_e32 v15, v58, v58
	v_max_f32_e32 v166, v74, v74
	v_max_f32_e32 v15, v166, v15
	v_max_f32_e32 v166, v59, v59
	v_max_f32_e32 v167, v75, v75
	v_max_f32_e32 v166, v167, v166
	v_max3_f32 v14, v14, v15, v166
	v_max_f32_e32 v15, v60, v60
	v_max_f32_e32 v166, v76, v76
	v_max_f32_e32 v15, v166, v15
	v_max_f32_e32 v166, v61, v61
	v_max_f32_e32 v167, v77, v77
	v_max_f32_e32 v166, v167, v166
	v_max3_f32 v14, v14, v15, v166
	v_max_f32_e32 v15, v62, v62
	v_max_f32_e32 v166, v78, v78
	v_max_f32_e32 v15, v166, v15
	v_max_f32_e32 v166, v63, v63
	v_max_f32_e32 v167, v79, v79
	v_max_f32_e32 v166, v167, v166
	v_max3_f32 v14, v14, v15, v166
	ds_bpermute_b32 v15, v159, v14
	v_mov_b32_e32 v168, v64
	v_mov_b32_e32 v169, v48
	v_mov_b32_e32 v64, v65
	v_mov_b32_e32 v65, v66
	s_waitcnt lgkmcnt(0)
	v_max3_f32 v14, v14, v15, 0
	v_mov_b32_e32 v48, v49
	v_mov_b32_e32 v49, v50
	v_pk_add_f32 v[170:171], v[64:65], v[14:15] op_sel_hi:[1,0] neg_lo:[0,1] neg_hi:[0,1]
	v_pk_add_f32 v[64:65], v[48:49], v[14:15] op_sel_hi:[1,0] neg_lo:[0,1] neg_hi:[0,1]
	v_mov_b32_e32 v48, v67
	v_mov_b32_e32 v49, v68
	v_pk_add_f32 v[172:173], v[48:49], v[14:15] op_sel_hi:[1,0] neg_lo:[0,1] neg_hi:[0,1]
	v_mov_b32_e32 v48, v51
	v_mov_b32_e32 v49, v52
	v_pk_add_f32 v[66:67], v[48:49], v[14:15] op_sel_hi:[1,0] neg_lo:[0,1] neg_hi:[0,1]
	v_mov_b32_e32 v48, v69
	v_mov_b32_e32 v49, v70
	v_pk_add_f32 v[174:175], v[48:49], v[14:15] op_sel_hi:[1,0] neg_lo:[0,1] neg_hi:[0,1]
	v_mov_b32_e32 v48, v53
	v_mov_b32_e32 v49, v54
	v_pk_add_f32 v[68:69], v[48:49], v[14:15] op_sel_hi:[1,0] neg_lo:[0,1] neg_hi:[0,1]
	v_mov_b32_e32 v48, v71
	v_mov_b32_e32 v49, v72
	v_pk_add_f32 v[176:177], v[48:49], v[14:15] op_sel_hi:[1,0] neg_lo:[0,1] neg_hi:[0,1]
	v_mov_b32_e32 v48, v55
	v_mov_b32_e32 v49, v56
	v_pk_add_f32 v[70:71], v[48:49], v[14:15] op_sel_hi:[1,0] neg_lo:[0,1] neg_hi:[0,1]
	v_mov_b32_e32 v48, v73
	v_mov_b32_e32 v49, v74
	v_pk_add_f32 v[178:179], v[48:49], v[14:15] op_sel_hi:[1,0] neg_lo:[0,1] neg_hi:[0,1]
	v_mov_b32_e32 v48, v57
	v_mov_b32_e32 v49, v58
	v_pk_add_f32 v[72:73], v[48:49], v[14:15] op_sel_hi:[1,0] neg_lo:[0,1] neg_hi:[0,1]
	v_mov_b32_e32 v48, v75
	v_mov_b32_e32 v49, v76
	v_exp_f32_e64 v166, -v14
	v_pk_add_f32 v[180:181], v[48:49], v[14:15] op_sel_hi:[1,0] neg_lo:[0,1] neg_hi:[0,1]
	v_mov_b32_e32 v48, v59
	v_mov_b32_e32 v49, v60
	v_pk_add_f32 v[74:75], v[48:49], v[14:15] op_sel_hi:[1,0] neg_lo:[0,1] neg_hi:[0,1]
	v_mov_b32_e32 v48, v77
	v_mov_b32_e32 v49, v78
	v_pk_add_f32 v[182:183], v[48:49], v[14:15] op_sel_hi:[1,0] neg_lo:[0,1] neg_hi:[0,1]
	v_mov_b32_e32 v48, v61
	v_mov_b32_e32 v49, v62
	v_pk_add_f32 v[168:169], v[168:169], v[14:15] op_sel_hi:[1,0] neg_lo:[0,1] neg_hi:[0,1]
	v_pk_add_f32 v[76:77], v[48:49], v[14:15] op_sel_hi:[1,0] neg_lo:[0,1] neg_hi:[0,1]
	v_add_f32_e32 v161, v161, v14
	v_xor_b32_e32 v218, 0x80000000, v161
	v_mov_b32_e32 v219, v218
	v_mov_b32_e32 v220, v218
	v_mov_b32_e32 v221, v218
	v_mov_b32_e32 v222, v218
	v_mov_b32_e32 v223, v218
	v_mov_b32_e32 v224, v218
	v_mov_b32_e32 v225, v218
	v_mov_b32_e32 v226, v218
	v_mov_b32_e32 v227, v218
	v_mov_b32_e32 v228, v218
	v_mov_b32_e32 v229, v218
	v_mov_b32_e32 v230, v218
	v_mov_b32_e32 v231, v218
	v_mov_b32_e32 v232, v218
	v_mov_b32_e32 v233, v218
	v_mul_f32_e32 v0, v0, v166
	v_pk_mul_f32 v[46:47], v[46:47], v[166:167] op_sel_hi:[1,0]
	v_pk_mul_f32 v[44:45], v[44:45], v[166:167] op_sel_hi:[1,0]
	v_pk_mul_f32 v[42:43], v[42:43], v[166:167] op_sel_hi:[1,0]
	v_pk_mul_f32 v[40:41], v[40:41], v[166:167] op_sel_hi:[1,0]
	v_pk_mul_f32 v[38:39], v[38:39], v[166:167] op_sel_hi:[1,0]
	v_pk_mul_f32 v[36:37], v[36:37], v[166:167] op_sel_hi:[1,0]
	v_pk_mul_f32 v[34:35], v[34:35], v[166:167] op_sel_hi:[1,0]
	v_pk_mul_f32 v[32:33], v[32:33], v[166:167] op_sel_hi:[1,0]
	v_pk_mul_f32 v[30:31], v[30:31], v[166:167] op_sel_hi:[1,0]
	v_pk_mul_f32 v[28:29], v[28:29], v[166:167] op_sel_hi:[1,0]
	v_pk_mul_f32 v[26:27], v[26:27], v[166:167] op_sel_hi:[1,0]
	v_pk_mul_f32 v[24:25], v[24:25], v[166:167] op_sel_hi:[1,0]
	v_pk_mul_f32 v[22:23], v[22:23], v[166:167] op_sel_hi:[1,0]
	v_pk_mul_f32 v[20:21], v[20:21], v[166:167] op_sel_hi:[1,0]
	v_pk_mul_f32 v[18:19], v[18:19], v[166:167] op_sel_hi:[1,0]
	v_pk_mul_f32 v[16:17], v[16:17], v[166:167] op_sel_hi:[1,0]
	v_sub_f32_e32 v79, v79, v14
	v_sub_f32_e32 v63, v63, v14
	v_mov_b32_e32 v49, v64
	v_mov_b32_e32 v50, v65
	v_mov_b32_e32 v51, v66
	v_mov_b32_e32 v52, v67
	v_mov_b32_e32 v53, v68
	v_mov_b32_e32 v54, v69
	v_mov_b32_e32 v55, v70
	v_mov_b32_e32 v56, v71
	v_mov_b32_e32 v57, v72
	v_mov_b32_e32 v58, v73
	v_mov_b32_e32 v59, v74
	v_mov_b32_e32 v60, v75
	v_mov_b32_e32 v61, v76
	v_mov_b32_e32 v62, v77
	v_mov_b32_e32 v65, v170
	v_mov_b32_e32 v66, v171
	v_mov_b32_e32 v67, v172
	v_mov_b32_e32 v68, v173
	v_mov_b32_e32 v69, v174
	v_mov_b32_e32 v70, v175
	v_mov_b32_e32 v71, v176
	v_mov_b32_e32 v72, v177
	v_mov_b32_e32 v73, v178
	v_mov_b32_e32 v74, v179
	v_mov_b32_e32 v75, v180
	v_mov_b32_e32 v76, v181
	v_mov_b32_e32 v77, v182
	v_mov_b32_e32 v78, v183
	v_mov_b32_e32 v64, v168
	v_mov_b32_e32 v48, v169
.LBB0_176:
	v_exp_f32_e32 v14, v64
	v_exp_f32_e32 v15, v48
	v_exp_f32_e32 v48, v65
	v_exp_f32_e32 v64, v66
	v_exp_f32_e32 v65, v67
	v_exp_f32_e32 v66, v68
	v_exp_f32_e32 v67, v69
	v_exp_f32_e32 v68, v70
	v_exp_f32_e32 v69, v71
	v_cvt_pk_bf16_f32 v166, v14, v48
	v_cvt_pk_bf16_f32 v167, v64, v65
	v_cvt_pk_bf16_f32 v168, v66, v67
	v_cvt_pk_bf16_f32 v169, v68, v69
	v_exp_f32_e32 v70, v72
	v_exp_f32_e32 v71, v73
	s_waitcnt lgkmcnt(0)
	v_mfma_f32_32x32x16_bf16 v[32:47], v[144:147], v[166:169], v[32:47]
	v_exp_f32_e32 v72, v74
	v_exp_f32_e32 v73, v75
	v_exp_f32_e32 v74, v76
	v_exp_f32_e32 v75, v77
	v_exp_f32_e32 v76, v78
	v_exp_f32_e32 v77, v79
	v_cvt_pk_bf16_f32 v170, v70, v71
	v_mfma_f32_32x32x16_bf16 v[16:31], v[128:131], v[166:169], v[16:31]
	v_cvt_pk_bf16_f32 v171, v72, v73
	v_cvt_pk_bf16_f32 v172, v74, v75
	v_cvt_pk_bf16_f32 v173, v76, v77
	v_exp_f32_e32 v49, v49
	v_exp_f32_e32 v50, v50
	v_exp_f32_e32 v51, v51
	v_exp_f32_e32 v52, v52
	v_mfma_f32_32x32x16_bf16 v[32:47], v[140:143], v[170:173], v[32:47]
	v_exp_f32_e32 v53, v53
	v_exp_f32_e32 v54, v54
	v_exp_f32_e32 v55, v55
	v_cvt_pk_bf16_f32 v174, v15, v49
	v_cvt_pk_bf16_f32 v175, v50, v51
	v_cvt_pk_bf16_f32 v176, v52, v53
	v_cvt_pk_bf16_f32 v177, v54, v55
	v_mfma_f32_32x32x16_bf16 v[16:31], v[10:13], v[170:173], v[16:31]
	v_exp_f32_e32 v56, v56
	v_exp_f32_e32 v57, v57
	v_exp_f32_e32 v58, v58
	v_exp_f32_e32 v59, v59
	v_exp_f32_e32 v60, v60
	v_exp_f32_e32 v61, v61
	v_exp_f32_e32 v62, v62
	v_mfma_f32_32x32x16_bf16 v[32:47], v[136:139], v[174:177], v[32:47]
	v_exp_f32_e32 v63, v63
	v_cvt_pk_bf16_f32 v178, v56, v57
	v_cvt_pk_bf16_f32 v179, v58, v59
	v_cvt_pk_bf16_f32 v180, v60, v61
	v_cvt_pk_bf16_f32 v181, v62, v63
	s_andn2_b64 vcc, exec, s[2:3]
	v_mfma_f32_32x32x16_bf16 v[16:31], v[2:5], v[174:177], v[16:31]
	v_mfma_f32_32x32x16_bf16 v[32:47], v[132:135], v[178:181], v[32:47]
	v_mfma_f32_32x32x16_bf16 v[16:31], v[6:9], v[178:181], v[16:31]
	s_cbranch_vccnz .LBB0_180
	ds_write_b128 v157, v[104:107]
	s_and_saveexec_b64 s[2:3], s[38:39]
	ds_write_b128 v158, v[112:115]
	s_or_b64 exec, exec, s[2:3]
	ds_write_b128 v160, v[120:123] offset:13312

.LBB0_184:
	s_lshl_b32 s2, s64, 2
	s_add_i32 s2, s2, s33
	s_mul_i32 s40, s2, 0x108000
	s_mul_hi_i32 s41, s2, 0x108000
	s_add_u32 s12, s77, s40
	s_addc_u32 s13, s71, s41
	s_add_u32 s22, s72, s40
	v_ashrrev_i32_e32 v0, 31, v148
	s_addc_u32 s23, s66, s41
	v_lshrrev_b32_e32 v0, 29, v0
	s_add_u32 s14, s24, s40
	v_add_u32_e32 v0, v148, v0
	s_addc_u32 s15, s76, s41
	v_ashrrev_i32_e32 v26, 3, v0
	v_and_b32_e32 v0, -8, v0
	s_and_b64 s[2:3], s[88:89], exec
	v_sub_u32_e32 v27, v148, v0
	v_lshlrev_b32_e32 v0, 6, v26
	s_cselect_b32 s3, 0, 0x2000
	v_lshl_add_u32 v2, v27, 3, v0
	v_mov_b64_e32 v[4:5], s[14:15]
	v_lshlrev_b32_e32 v0, 4, v148
	s_cselect_b32 s2, 0x84, 4
	v_mad_i64_i32 v[4:5], s[14:15], v156, s54, v[4:5]
	v_and_b32_e32 v18, 0x70, v0
	v_mov_b32_e32 v19, v1
	s_lshl_b32 s38, s3, 7
	v_lshl_add_u64 v[4:5], v[4:5], 0, v[18:19]
	s_add_u32 s14, s22, s38
	v_ashrrev_i32_e32 v3, 31, v2
	v_lshrrev_b32_e32 v6, 1, v148
	v_and_b32_e32 v19, 31, v148
	s_addc_u32 s15, s23, 0
	v_lshlrev_b64 v[20:21], 1, v[2:3]
	v_and_or_b32 v0, v6, s5, v19
	v_lshl_add_u64 v[2:3], s[14:15], 0, v[20:21]
	s_lshl_b32 s96, s3, 1
	v_and_b32_e32 v22, 0xffffffe0, v156
	v_add_lshl_u32 v0, v0, s65, 7
	v_lshl_add_u64 v[4:5], v[4:5], 0, s[96:97]
	global_load_dwordx4 v[66:69], v[2:3], off
	global_load_dwordx4 v[78:81], v[4:5], off
	v_lshl_add_u64 v[2:3], s[12:13], 0, v[0:1]
	v_ashrrev_i32_e32 v23, 31, v22
	s_or_b32 s3, s38, 0x2000
	v_lshl_add_u64 v[2:3], v[22:23], 1, v[2:3]
	v_and_b32_e32 v0, 16, v6
	s_add_u32 s12, s22, s3
	v_lshl_add_u64 v[2:3], v[2:3], 0, v[0:1]
	s_addc_u32 s13, s23, 0
	global_load_dwordx4 v[70:73], v[2:3], off
	global_load_dwordx4 v[74:77], v[2:3], off offset:32
	v_lshl_add_u64 v[2:3], s[12:13], 0, v[20:21]
	global_load_dwordx4 v[86:89], v[4:5], off offset:128
	global_load_dwordx4 v[82:85], v[2:3], off
	v_mad_i64_i32 v[24:25], s[12:13], v156, s54, 0
	v_mad_u64_u32 v[122:123], s[12:13], v156, s4, v[18:19]
	s_add_u32 s12, s36, s96
	v_or_b32_e32 v24, v24, v18
	s_addc_u32 s13, s37, 0
	v_cmp_lt_i32_e32 vcc, v207, v206
	s_waitcnt vmcnt(14)
	v_lshl_add_u64 v[124:125], s[12:13], 0, v[24:25]
	s_add_u32 s12, s36, s38
	v_cndmask_b32_e32 v23, v205, v207, vcc
	v_mul_u32_u24_e32 v133, 0x90, v19
	v_mul_lo_u32 v18, v26, s4
	v_lshl_or_b32 v34, v22, 1, v0
	s_addc_u32 s13, s37, 0
	s_mov_b32 s3, 3
	v_mov_b32_e32 v2, v1
	v_mov_b32_e32 v3, v1
	v_mov_b32_e32 v4, v1
	v_mov_b32_e32 v5, v1
	v_mov_b32_e32 v6, v1
	v_mov_b32_e32 v7, v1
	v_mov_b32_e32 v8, v1
	v_mov_b32_e32 v9, v1
	v_mov_b32_e32 v10, v1
	v_mov_b32_e32 v11, v1
	v_mov_b32_e32 v12, v1
	v_mov_b32_e32 v13, v1
	v_mov_b32_e32 v14, v1
	v_mov_b32_e32 v15, v1
	v_mov_b32_e32 v16, v1
	v_mov_b32_e32 v17, v1
	v_lshlrev_b32_e32 v132, 2, v23
	v_lshl_add_u32 v123, v27, 4, v18
	v_lshl_add_u64 v[126:127], s[12:13], 0, v[20:21]
	v_mov_b32_e32 v18, v1
	v_mov_b32_e32 v19, v1
	v_mov_b32_e32 v20, v1
	v_mov_b32_e32 v21, v1
	v_mov_b32_e32 v22, v1
	v_mov_b32_e32 v23, v1
	v_mov_b32_e32 v24, v1
	v_mov_b32_e32 v25, v1
	v_mov_b32_e32 v26, v1
	v_mov_b32_e32 v27, v1
	v_mov_b32_e32 v28, v1
	v_mov_b32_e32 v29, v1
	v_mov_b32_e32 v30, v1
	v_mov_b32_e32 v31, v1
	v_mov_b32_e32 v32, v1
	v_mov_b32_e32 v33, v1
	v_mov_b32_e32 v134, 0
	v_bfrev_b32_e32 v218, 1
	v_mov_b32_e32 v219, v218
	v_mov_b32_e32 v220, v218
	v_mov_b32_e32 v221, v218
	v_mov_b32_e32 v222, v218
	v_mov_b32_e32 v223, v218
	v_mov_b32_e32 v224, v218
	v_mov_b32_e32 v225, v218
	v_mov_b32_e32 v226, v218
	v_mov_b32_e32 v227, v218
	v_mov_b32_e32 v228, v218
	v_mov_b32_e32 v229, v218
	v_mov_b32_e32 v230, v218
	v_mov_b32_e32 v231, v218
	v_mov_b32_e32 v232, v218
	v_mov_b32_e32 v233, v218
	v_add_u32_e32 v135, v133, v34
	v_mov_b32_e32 v136, 0
	s_waitcnt vmcnt(5)
	ds_write_b128 v123, v[66:69]
	s_waitcnt vmcnt(4)
	ds_write_b128 v122, v[78:81] offset:9216
	s_waitcnt lgkmcnt(0)
	s_barrier
	s_branch .LBB0_186

.LBB0_188:
	ds_read_b128 v[90:93], v135
	ds_read_b128 v[94:97], v135 offset:32
	ds_read_b128 v[98:101], v135 offset:4608
	ds_read_b128 v[138:141], v135 offset:4640
	s_cmp_eq_u32 s3, 3
	s_cselect_b64 s[38:39], -1, 0
	s_waitcnt vmcnt(3) lgkmcnt(3)
	s_nop 0
	v_mfma_f32_32x32x16_bf16 v[50:65], v[90:93], v[70:73], v[218:233]
	v_add_u32_e32 v137, v133, v0
	s_waitcnt lgkmcnt(1)
	v_mfma_f32_32x32x16_bf16 v[34:49], v[98:101], v[70:73], v[218:233]
	s_waitcnt vmcnt(2)
	v_mfma_f32_32x32x16_bf16 v[50:65], v[94:97], v[74:77], v[50:65]
	ds_read_b128 v[118:121], v137 offset:9216
	ds_read_b128 v[114:117], v137 offset:9248
	ds_read_b128 v[110:113], v137 offset:9280
	ds_read_b128 v[106:109], v137 offset:9312
	ds_read_b128 v[102:105], v137 offset:13824
	ds_read_b128 v[98:101], v137 offset:13856
	ds_read_b128 v[90:93], v137 offset:13888
	ds_read_b128 v[94:97], v137 offset:13920
	s_waitcnt lgkmcnt(8)
	v_mfma_f32_32x32x16_bf16 v[34:49], v[138:141], v[74:77], v[34:49]
	s_nop 1
	v_max_i32_e32 v138, v50, v51
	s_nop 8
	v_max3_i32 v138, v138, v34, v35
	v_max3_i32 v138, v138, v52, v53
	v_max3_i32 v138, v138, v36, v37
	v_max3_i32 v138, v138, v54, v55
	v_max3_i32 v138, v138, v38, v39
	v_max3_i32 v138, v138, v56, v57
	v_max3_i32 v138, v138, v40, v41
	v_max3_i32 v138, v138, v58, v59
	v_max3_i32 v138, v138, v42, v43
	v_max3_i32 v138, v138, v60, v61
	v_max3_i32 v138, v138, v44, v45
	v_max3_i32 v138, v138, v62, v63
	v_max3_i32 v138, v138, v46, v47
	v_max3_i32 v138, v138, v64, v65
	v_max3_i32 v138, v138, v48, v49
	v_cmp_lt_i32_e32 vcc, s74, v138
	s_or_b64 vcc, s[38:39], vcc
	s_cbranch_vccz .LBB0_190
	v_max_f32_e32 v138, v35, v35
	v_max_f32_e32 v139, v51, v51
	v_max_f32_e32 v138, v139, v138
	v_max_f32_e32 v139, v36, v36
	v_max_f32_e32 v140, v52, v52
	v_max_f32_e32 v139, v140, v139
	v_max_f32_e32 v140, v37, v37
	v_max_f32_e32 v141, v53, v53
	v_max3_f32 v138, v50, v34, v138
	v_max_f32_e32 v140, v141, v140
	v_max3_f32 v138, v138, v139, v140
	v_max_f32_e32 v139, v38, v38
	v_max_f32_e32 v140, v54, v54
	v_max_f32_e32 v139, v140, v139
	v_max_f32_e32 v140, v39, v39
	v_max_f32_e32 v141, v55, v55
	v_max_f32_e32 v140, v141, v140
	v_max3_f32 v138, v138, v139, v140
	v_max_f32_e32 v139, v40, v40
	v_max_f32_e32 v140, v56, v56
	v_max_f32_e32 v139, v140, v139
	v_max_f32_e32 v140, v41, v41
	v_max_f32_e32 v141, v57, v57
	v_max_f32_e32 v140, v141, v140
	v_max3_f32 v138, v138, v139, v140
	v_max_f32_e32 v139, v42, v42
	v_max_f32_e32 v140, v58, v58
	v_max_f32_e32 v139, v140, v139
	v_max_f32_e32 v140, v43, v43
	v_max_f32_e32 v141, v59, v59
	v_max_f32_e32 v140, v141, v140
	v_max3_f32 v138, v138, v139, v140
	v_max_f32_e32 v139, v44, v44
	v_max_f32_e32 v140, v60, v60
	v_max_f32_e32 v139, v140, v139
	v_max_f32_e32 v140, v45, v45
	v_max_f32_e32 v141, v61, v61
	v_max_f32_e32 v140, v141, v140
	v_max3_f32 v138, v138, v139, v140
	v_max_f32_e32 v139, v46, v46
	v_max_f32_e32 v140, v62, v62
	v_max_f32_e32 v139, v140, v139
	v_max_f32_e32 v140, v47, v47
	v_max_f32_e32 v141, v63, v63
	v_max_f32_e32 v140, v141, v140
	v_max3_f32 v138, v138, v139, v140
	v_max_f32_e32 v139, v48, v48
	v_max_f32_e32 v140, v64, v64
	v_max_f32_e32 v139, v140, v139
	v_max_f32_e32 v140, v49, v49
	v_max_f32_e32 v141, v65, v65
	v_max_f32_e32 v140, v141, v140
	v_max3_f32 v138, v138, v139, v140
	ds_bpermute_b32 v139, v132, v138
	v_mov_b32_e32 v140, v50
	v_mov_b32_e32 v50, v51
	v_mov_b32_e32 v51, v52
	v_mov_b32_e32 v52, v53
	s_waitcnt lgkmcnt(0)
	v_max_f32_e32 v139, v139, v139
	v_max_f32_e32 v138, v138, v139
	v_max_f32_e32 v139, 0, v138
	v_cndmask_b32_e64 v138, v139, v138, s[38:39]
	v_exp_f32_e64 v139, -v138
	v_mov_b32_e32 v53, v54
	v_mov_b32_e32 v141, v34
	v_add_f32_e32 v134, v134, v138
	v_xor_b32_e32 v218, 0x80000000, v134
	v_mov_b32_e32 v219, v218
	v_mov_b32_e32 v220, v218
	v_mov_b32_e32 v221, v218
	v_mov_b32_e32 v222, v218
	v_mov_b32_e32 v223, v218
	v_mov_b32_e32 v224, v218
	v_mov_b32_e32 v225, v218
	v_mov_b32_e32 v226, v218
	v_mov_b32_e32 v227, v218
	v_mov_b32_e32 v228, v218
	v_mov_b32_e32 v229, v218
	v_mov_b32_e32 v230, v218
	v_mov_b32_e32 v231, v218
	v_mov_b32_e32 v232, v218
	v_mov_b32_e32 v233, v218
	v_pk_add_f32 v[142:143], v[50:51], v[138:139] op_sel_hi:[1,0] neg_lo:[0,1] neg_hi:[0,1]
	v_mov_b32_e32 v51, v36
	v_mov_b32_e32 v36, v37
	v_mov_b32_e32 v37, v38
	v_pk_add_f32 v[144:145], v[52:53], v[138:139] op_sel_hi:[1,0] neg_lo:[0,1] neg_hi:[0,1]
	v_pk_add_f32 v[52:53], v[36:37], v[138:139] op_sel_hi:[1,0] neg_lo:[0,1] neg_hi:[0,1]
	v_mov_b32_e32 v36, v55
	v_mov_b32_e32 v37, v56
	v_pk_add_f32 v[146:147], v[36:37], v[138:139] op_sel_hi:[1,0] neg_lo:[0,1] neg_hi:[0,1]
	v_mov_b32_e32 v36, v39
	v_mov_b32_e32 v37, v40
	v_pk_add_f32 v[54:55], v[36:37], v[138:139] op_sel_hi:[1,0] neg_lo:[0,1] neg_hi:[0,1]
	v_mov_b32_e32 v36, v57
	v_mov_b32_e32 v37, v58
	v_pk_add_f32 v[150:151], v[36:37], v[138:139] op_sel_hi:[1,0] neg_lo:[0,1] neg_hi:[0,1]
	v_mov_b32_e32 v36, v41
	v_mov_b32_e32 v37, v42
	v_pk_add_f32 v[56:57], v[36:37], v[138:139] op_sel_hi:[1,0] neg_lo:[0,1] neg_hi:[0,1]
	v_mov_b32_e32 v36, v59
	v_mov_b32_e32 v37, v60
	v_pk_add_f32 v[152:153], v[36:37], v[138:139] op_sel_hi:[1,0] neg_lo:[0,1] neg_hi:[0,1]
	v_mov_b32_e32 v36, v43
	v_mov_b32_e32 v37, v44
	v_pk_add_f32 v[58:59], v[36:37], v[138:139] op_sel_hi:[1,0] neg_lo:[0,1] neg_hi:[0,1]
	v_mov_b32_e32 v36, v61
	v_mov_b32_e32 v37, v62
	v_pk_add_f32 v[154:155], v[36:37], v[138:139] op_sel_hi:[1,0] neg_lo:[0,1] neg_hi:[0,1]
	v_mov_b32_e32 v36, v45
	v_mov_b32_e32 v37, v46
	v_pk_add_f32 v[60:61], v[36:37], v[138:139] op_sel_hi:[1,0] neg_lo:[0,1] neg_hi:[0,1]
	v_mov_b32_e32 v36, v63
	v_mov_b32_e32 v37, v64
	v_mov_b32_e32 v50, v35
	v_pk_add_f32 v[156:157], v[36:37], v[138:139] op_sel_hi:[1,0] neg_lo:[0,1] neg_hi:[0,1]
	v_mov_b32_e32 v36, v47
	v_mov_b32_e32 v37, v48
	v_cndmask_b32_e64 v34, v139, 1.0, s[38:39]
	v_pk_add_f32 v[140:141], v[140:141], v[138:139] op_sel_hi:[1,0] neg_lo:[0,1] neg_hi:[0,1]
	v_pk_add_f32 v[50:51], v[50:51], v[138:139] op_sel_hi:[1,0] neg_lo:[0,1] neg_hi:[0,1]
	v_pk_add_f32 v[62:63], v[36:37], v[138:139] op_sel_hi:[1,0] neg_lo:[0,1] neg_hi:[0,1]
	v_mul_f32_e32 v136, v136, v34
	v_sub_f32_e32 v65, v65, v138
	v_sub_f32_e32 v49, v49, v138
	v_pk_mul_f32 v[32:33], v[32:33], v[34:35] op_sel_hi:[1,0]
	v_pk_mul_f32 v[30:31], v[30:31], v[34:35] op_sel_hi:[1,0]
	v_pk_mul_f32 v[28:29], v[28:29], v[34:35] op_sel_hi:[1,0]
	v_pk_mul_f32 v[26:27], v[26:27], v[34:35] op_sel_hi:[1,0]
	v_pk_mul_f32 v[24:25], v[24:25], v[34:35] op_sel_hi:[1,0]
	v_pk_mul_f32 v[22:23], v[22:23], v[34:35] op_sel_hi:[1,0]
	v_pk_mul_f32 v[20:21], v[20:21], v[34:35] op_sel_hi:[1,0]
	v_pk_mul_f32 v[18:19], v[18:19], v[34:35] op_sel_hi:[1,0]
	v_pk_mul_f32 v[16:17], v[16:17], v[34:35] op_sel_hi:[1,0]
	v_pk_mul_f32 v[14:15], v[14:15], v[34:35] op_sel_hi:[1,0]
	v_pk_mul_f32 v[12:13], v[12:13], v[34:35] op_sel_hi:[1,0]
	v_pk_mul_f32 v[10:11], v[10:11], v[34:35] op_sel_hi:[1,0]
	v_pk_mul_f32 v[8:9], v[8:9], v[34:35] op_sel_hi:[1,0]
	v_pk_mul_f32 v[6:7], v[6:7], v[34:35] op_sel_hi:[1,0]
	v_pk_mul_f32 v[4:5], v[4:5], v[34:35] op_sel_hi:[1,0]
	v_pk_mul_f32 v[2:3], v[2:3], v[34:35] op_sel_hi:[1,0]
	v_mov_b32_e32 v35, v50
	v_mov_b32_e32 v36, v51
	v_mov_b32_e32 v37, v52
	v_mov_b32_e32 v38, v53
	v_mov_b32_e32 v39, v54
	v_mov_b32_e32 v40, v55
	v_mov_b32_e32 v41, v56
	v_mov_b32_e32 v42, v57
	v_mov_b32_e32 v43, v58
	v_mov_b32_e32 v44, v59
	v_mov_b32_e32 v45, v60
	v_mov_b32_e32 v46, v61
	v_mov_b32_e32 v47, v62
	v_mov_b32_e32 v48, v63
	v_mov_b32_e32 v51, v142
	v_mov_b32_e32 v52, v143
	v_mov_b32_e32 v53, v144
	v_mov_b32_e32 v54, v145
	v_mov_b32_e32 v55, v146
	v_mov_b32_e32 v56, v147
	v_mov_b32_e32 v57, v150
	v_mov_b32_e32 v58, v151
	v_mov_b32_e32 v59, v152
	v_mov_b32_e32 v60, v153
	v_mov_b32_e32 v61, v154
	v_mov_b32_e32 v62, v155
	v_mov_b32_e32 v63, v156
	v_mov_b32_e32 v64, v157
	v_mov_b32_e32 v50, v140
	v_mov_b32_e32 v34, v141
.LBB0_190:
	v_exp_f32_e32 v50, v50
	v_exp_f32_e32 v51, v51
	v_exp_f32_e32 v52, v52
	v_exp_f32_e32 v53, v53
	v_exp_f32_e32 v54, v54
	v_exp_f32_e32 v55, v55
	v_exp_f32_e32 v56, v56
	v_exp_f32_e32 v57, v57
	v_cvt_pk_bf16_f32 v138, v50, v51
	v_cvt_pk_bf16_f32 v139, v52, v53
	v_cvt_pk_bf16_f32 v140, v54, v55
	v_cvt_pk_bf16_f32 v141, v56, v57
	v_exp_f32_e32 v58, v58
	v_exp_f32_e32 v59, v59
	s_waitcnt lgkmcnt(0)
	v_mfma_f32_32x32x16_bf16 v[2:17], v[118:121], v[138:141], v[2:17]
	v_exp_f32_e32 v60, v60
	v_exp_f32_e32 v61, v61
	v_exp_f32_e32 v62, v62
	v_exp_f32_e32 v63, v63
	v_exp_f32_e32 v64, v64
	v_exp_f32_e32 v65, v65
	v_cvt_pk_bf16_f32 v142, v58, v59
	v_mfma_f32_32x32x16_bf16 v[18:33], v[102:105], v[138:141], v[18:33]
	v_cvt_pk_bf16_f32 v143, v60, v61
	v_cvt_pk_bf16_f32 v144, v62, v63
	v_cvt_pk_bf16_f32 v145, v64, v65
	v_exp_f32_e32 v34, v34
	v_exp_f32_e32 v35, v35
	v_exp_f32_e32 v36, v36
	v_exp_f32_e32 v37, v37
	v_mfma_f32_32x32x16_bf16 v[2:17], v[114:117], v[142:145], v[2:17]
	v_exp_f32_e32 v38, v38
	v_exp_f32_e32 v39, v39
	v_exp_f32_e32 v40, v40
	v_exp_f32_e32 v41, v41
	v_cvt_pk_bf16_f32 v150, v34, v35
	v_cvt_pk_bf16_f32 v151, v36, v37
	v_cvt_pk_bf16_f32 v152, v38, v39
	v_mfma_f32_32x32x16_bf16 v[18:33], v[98:101], v[142:145], v[18:33]
	v_cvt_pk_bf16_f32 v153, v40, v41
	v_exp_f32_e32 v42, v42
	v_exp_f32_e32 v43, v43
	v_exp_f32_e32 v44, v44
	v_exp_f32_e32 v45, v45
	v_exp_f32_e32 v46, v46
	v_exp_f32_e32 v47, v47
	v_mfma_f32_32x32x16_bf16 v[2:17], v[110:113], v[150:153], v[2:17]
	v_exp_f32_e32 v48, v48
	v_exp_f32_e32 v49, v49
	v_cvt_pk_bf16_f32 v154, v42, v43
	v_cvt_pk_bf16_f32 v155, v44, v45
	v_cvt_pk_bf16_f32 v156, v46, v47
	v_cvt_pk_bf16_f32 v157, v48, v49
	s_cmp_ge_u32 s3, s2
	v_mfma_f32_32x32x16_bf16 v[18:33], v[90:93], v[150:153], v[18:33]
	s_waitcnt vmcnt(0)
	ds_write_b128 v123, v[82:85] offset:18432
	ds_write_b128 v122, v[86:89] offset:27648
	s_waitcnt lgkmcnt(0)
	s_barrier
	v_mfma_f32_32x32x16_bf16 v[2:17], v[106:109], v[154:157], v[2:17]
	v_mfma_f32_32x32x16_bf16 v[18:33], v[94:97], v[154:157], v[18:33]
	s_cbranch_scc1 .LBB0_192
	v_add_co_u32_e32 v82, vcc, 0x6e73000, v130
	s_nop 1
	v_addc_co_u32_e32 v83, vcc, 0, v131, vcc
	v_add_co_u32_e32 v86, vcc, 0x76ad000, v128
	global_load_dwordx4 v[82:85], v[82:83], off offset:2048
	s_nop 0
	v_addc_co_u32_e32 v87, vcc, 0, v129, vcc
	global_load_dwordx4 v[86:89], v[86:87], off offset:2432
.LBB0_192:
	v_add_f32_e32 v50, 0, v50
	v_add_f32_e32 v34, 0, v34
	v_add_f32_e32 v50, v50, v51
	v_add_f32_e32 v34, v34, v35
	v_add_f32_e32 v35, v52, v50
	v_add_f32_e32 v34, v36, v34
	v_add_f32_e32 v35, v53, v35
	v_add_f32_e32 v34, v37, v34
	v_add_f32_e32 v35, v54, v35
	v_add_f32_e32 v34, v38, v34
	v_add_f32_e32 v35, v55, v35
	v_add_f32_e32 v34, v39, v34
	v_add_f32_e32 v35, v56, v35
	v_add_f32_e32 v34, v40, v34
	v_add_f32_e32 v35, v57, v35
	v_add_f32_e32 v34, v41, v34
	v_add_f32_e32 v35, v58, v35
	v_add_f32_e32 v34, v42, v34
	v_add_f32_e32 v35, v59, v35
	v_add_f32_e32 v34, v43, v34
	v_add_f32_e32 v35, v60, v35
	v_add_f32_e32 v34, v44, v34
	v_add_f32_e32 v35, v61, v35
	v_add_f32_e32 v34, v45, v34
	v_add_f32_e32 v35, v62, v35
	v_add_f32_e32 v34, v46, v34
	ds_read_b128 v[90:93], v135 offset:18432
	ds_read_b128 v[94:97], v135 offset:18464
	ds_read_b128 v[98:101], v135 offset:23040
	ds_read_b128 v[138:141], v135 offset:23072
	v_add_f32_e32 v35, v63, v35
	v_add_f32_e32 v34, v47, v34
	v_add_f32_e32 v35, v64, v35
	v_add_f32_e32 v34, v48, v34
	v_add_f32_e32 v35, v65, v35
	v_add_f32_e32 v34, v49, v34
	v_add_f32_e32 v34, v34, v35
	v_add_f32_e32 v128, v136, v34
	s_waitcnt lgkmcnt(3)
	s_nop 0
	v_mfma_f32_32x32x16_bf16 v[50:65], v[90:93], v[70:73], v[218:233]
	s_waitcnt lgkmcnt(1)
	v_mfma_f32_32x32x16_bf16 v[34:49], v[98:101], v[70:73], v[218:233]
	v_mfma_f32_32x32x16_bf16 v[50:65], v[94:97], v[74:77], v[50:65]
	ds_read_b128 v[118:121], v137 offset:27648
	ds_read_b128 v[114:117], v137 offset:27680
	ds_read_b128 v[110:113], v137 offset:27712
	ds_read_b128 v[106:109], v137 offset:27744
	ds_read_b128 v[102:105], v137 offset:32256
	ds_read_b128 v[98:101], v137 offset:32288
	ds_read_b128 v[90:93], v137 offset:32320
	ds_read_b128 v[94:97], v137 offset:32352
	s_waitcnt lgkmcnt(8)
	v_mfma_f32_32x32x16_bf16 v[34:49], v[138:141], v[74:77], v[34:49]
	s_nop 1
	v_max_i32_e32 v129, v50, v51
	s_nop 8
	v_max3_i32 v129, v129, v34, v35
	v_max3_i32 v129, v129, v52, v53
	v_max3_i32 v129, v129, v36, v37
	v_max3_i32 v129, v129, v54, v55
	v_max3_i32 v129, v129, v38, v39
	v_max3_i32 v129, v129, v56, v57
	v_max3_i32 v129, v129, v40, v41
	v_max3_i32 v129, v129, v58, v59
	v_max3_i32 v129, v129, v42, v43
	v_max3_i32 v129, v129, v60, v61
	v_max3_i32 v129, v129, v44, v45
	v_max3_i32 v129, v129, v62, v63
	v_max3_i32 v129, v129, v46, v47
	v_max3_i32 v129, v129, v64, v65
	v_max3_i32 v129, v129, v48, v49
	v_cmp_lt_i32_e32 vcc, s74, v129
	s_cbranch_vccz .LBB0_194
	v_max_f32_e32 v129, v35, v35
	v_max_f32_e32 v130, v51, v51
	v_max_f32_e32 v129, v130, v129
	v_max_f32_e32 v130, v36, v36
	v_max_f32_e32 v131, v52, v52
	v_max_f32_e32 v130, v131, v130
	v_max_f32_e32 v131, v37, v37
	v_max_f32_e32 v136, v53, v53
	v_max3_f32 v129, v50, v34, v129
	v_max_f32_e32 v131, v136, v131
	v_max3_f32 v129, v129, v130, v131
	v_max_f32_e32 v130, v38, v38
	v_max_f32_e32 v131, v54, v54
	v_max_f32_e32 v130, v131, v130
	v_max_f32_e32 v131, v39, v39
	v_max_f32_e32 v136, v55, v55
	v_max_f32_e32 v131, v136, v131
	v_max3_f32 v129, v129, v130, v131
	v_max_f32_e32 v130, v40, v40
	v_max_f32_e32 v131, v56, v56
	v_max_f32_e32 v130, v131, v130
	v_max_f32_e32 v131, v41, v41
	v_max_f32_e32 v136, v57, v57
	v_max_f32_e32 v131, v136, v131
	v_max3_f32 v129, v129, v130, v131
	v_max_f32_e32 v130, v42, v42
	v_max_f32_e32 v131, v58, v58
	v_max_f32_e32 v130, v131, v130
	v_max_f32_e32 v131, v43, v43
	v_max_f32_e32 v136, v59, v59
	v_max_f32_e32 v131, v136, v131
	v_max3_f32 v129, v129, v130, v131
	v_max_f32_e32 v130, v44, v44
	v_max_f32_e32 v131, v60, v60
	v_max_f32_e32 v130, v131, v130
	v_max_f32_e32 v131, v45, v45
	v_max_f32_e32 v136, v61, v61
	v_max_f32_e32 v131, v136, v131
	v_max3_f32 v129, v129, v130, v131
	v_max_f32_e32 v130, v46, v46
	v_max_f32_e32 v131, v62, v62
	v_max_f32_e32 v130, v131, v130
	v_max_f32_e32 v131, v47, v47
	v_max_f32_e32 v136, v63, v63
	v_max_f32_e32 v131, v136, v131
	v_max3_f32 v129, v129, v130, v131
	v_max_f32_e32 v130, v48, v48
	v_max_f32_e32 v131, v64, v64
	v_max_f32_e32 v130, v131, v130
	v_max_f32_e32 v131, v49, v49
	v_max_f32_e32 v136, v65, v65
	v_max_f32_e32 v131, v136, v131
	v_max3_f32 v129, v129, v130, v131
	ds_bpermute_b32 v130, v132, v129
	v_mov_b32_e32 v138, v50
	v_mov_b32_e32 v139, v34
	v_mov_b32_e32 v50, v51
	v_mov_b32_e32 v51, v52
	s_waitcnt lgkmcnt(0)
	v_max3_f32 v130, v129, v130, 0
	v_mov_b32_e32 v34, v35
	v_mov_b32_e32 v35, v36
	v_pk_add_f32 v[140:141], v[50:51], v[130:131] op_sel_hi:[1,0] neg_lo:[0,1] neg_hi:[0,1]
	v_pk_add_f32 v[50:51], v[34:35], v[130:131] op_sel_hi:[1,0] neg_lo:[0,1] neg_hi:[0,1]
	v_mov_b32_e32 v34, v53
	v_mov_b32_e32 v35, v54
	v_pk_add_f32 v[142:143], v[34:35], v[130:131] op_sel_hi:[1,0] neg_lo:[0,1] neg_hi:[0,1]
	v_mov_b32_e32 v34, v37
	v_mov_b32_e32 v35, v38
	v_pk_add_f32 v[52:53], v[34:35], v[130:131] op_sel_hi:[1,0] neg_lo:[0,1] neg_hi:[0,1]
	v_mov_b32_e32 v34, v55
	v_mov_b32_e32 v35, v56
	v_pk_add_f32 v[144:145], v[34:35], v[130:131] op_sel_hi:[1,0] neg_lo:[0,1] neg_hi:[0,1]
	v_mov_b32_e32 v34, v39
	v_mov_b32_e32 v35, v40
	v_pk_add_f32 v[54:55], v[34:35], v[130:131] op_sel_hi:[1,0] neg_lo:[0,1] neg_hi:[0,1]
	v_mov_b32_e32 v34, v57
	v_mov_b32_e32 v35, v58
	v_pk_add_f32 v[146:147], v[34:35], v[130:131] op_sel_hi:[1,0] neg_lo:[0,1] neg_hi:[0,1]
	v_mov_b32_e32 v34, v41
	v_mov_b32_e32 v35, v42
	v_pk_add_f32 v[56:57], v[34:35], v[130:131] op_sel_hi:[1,0] neg_lo:[0,1] neg_hi:[0,1]
	v_mov_b32_e32 v34, v59
	v_mov_b32_e32 v35, v60
	v_pk_add_f32 v[150:151], v[34:35], v[130:131] op_sel_hi:[1,0] neg_lo:[0,1] neg_hi:[0,1]
	v_mov_b32_e32 v34, v43
	v_mov_b32_e32 v35, v44
	v_pk_add_f32 v[58:59], v[34:35], v[130:131] op_sel_hi:[1,0] neg_lo:[0,1] neg_hi:[0,1]
	v_mov_b32_e32 v34, v61
	v_mov_b32_e32 v35, v62
	v_exp_f32_e64 v136, -v130
	v_pk_add_f32 v[152:153], v[34:35], v[130:131] op_sel_hi:[1,0] neg_lo:[0,1] neg_hi:[0,1]
	v_mov_b32_e32 v34, v45
	v_mov_b32_e32 v35, v46
	v_pk_add_f32 v[60:61], v[34:35], v[130:131] op_sel_hi:[1,0] neg_lo:[0,1] neg_hi:[0,1]
	v_mov_b32_e32 v34, v63
	v_mov_b32_e32 v35, v64
	v_pk_add_f32 v[154:155], v[34:35], v[130:131] op_sel_hi:[1,0] neg_lo:[0,1] neg_hi:[0,1]
	v_mov_b32_e32 v34, v47
	v_mov_b32_e32 v35, v48
	v_pk_add_f32 v[138:139], v[138:139], v[130:131] op_sel_hi:[1,0] neg_lo:[0,1] neg_hi:[0,1]
	v_pk_add_f32 v[62:63], v[34:35], v[130:131] op_sel_hi:[1,0] neg_lo:[0,1] neg_hi:[0,1]
	v_add_f32_e32 v134, v134, v130
	v_xor_b32_e32 v218, 0x80000000, v134
	v_mov_b32_e32 v219, v218
	v_mov_b32_e32 v220, v218
	v_mov_b32_e32 v221, v218
	v_mov_b32_e32 v222, v218
	v_mov_b32_e32 v223, v218
	v_mov_b32_e32 v224, v218
	v_mov_b32_e32 v225, v218
	v_mov_b32_e32 v226, v218
	v_mov_b32_e32 v227, v218
	v_mov_b32_e32 v228, v218
	v_mov_b32_e32 v229, v218
	v_mov_b32_e32 v230, v218
	v_mov_b32_e32 v231, v218
	v_mov_b32_e32 v232, v218
	v_mov_b32_e32 v233, v218
	v_mul_f32_e32 v128, v128, v136
	v_sub_f32_e32 v65, v65, v130
	v_sub_f32_e32 v49, v49, v130
	v_pk_mul_f32 v[32:33], v[32:33], v[136:137] op_sel_hi:[1,0]
	v_pk_mul_f32 v[30:31], v[30:31], v[136:137] op_sel_hi:[1,0]
	v_pk_mul_f32 v[28:29], v[28:29], v[136:137] op_sel_hi:[1,0]
	v_pk_mul_f32 v[26:27], v[26:27], v[136:137] op_sel_hi:[1,0]
	v_pk_mul_f32 v[24:25], v[24:25], v[136:137] op_sel_hi:[1,0]
	v_pk_mul_f32 v[22:23], v[22:23], v[136:137] op_sel_hi:[1,0]
	v_pk_mul_f32 v[20:21], v[20:21], v[136:137] op_sel_hi:[1,0]
	v_pk_mul_f32 v[18:19], v[18:19], v[136:137] op_sel_hi:[1,0]
	v_pk_mul_f32 v[16:17], v[16:17], v[136:137] op_sel_hi:[1,0]
	v_pk_mul_f32 v[14:15], v[14:15], v[136:137] op_sel_hi:[1,0]
	v_pk_mul_f32 v[12:13], v[12:13], v[136:137] op_sel_hi:[1,0]
	v_pk_mul_f32 v[10:11], v[10:11], v[136:137] op_sel_hi:[1,0]
	v_pk_mul_f32 v[8:9], v[8:9], v[136:137] op_sel_hi:[1,0]
	v_pk_mul_f32 v[6:7], v[6:7], v[136:137] op_sel_hi:[1,0]
	v_pk_mul_f32 v[4:5], v[4:5], v[136:137] op_sel_hi:[1,0]
	v_pk_mul_f32 v[2:3], v[2:3], v[136:137] op_sel_hi:[1,0]
	v_mov_b32_e32 v35, v50
	v_mov_b32_e32 v36, v51
	v_mov_b32_e32 v37, v52
	v_mov_b32_e32 v38, v53
	v_mov_b32_e32 v39, v54
	v_mov_b32_e32 v40, v55
	v_mov_b32_e32 v41, v56
	v_mov_b32_e32 v42, v57
	v_mov_b32_e32 v43, v58
	v_mov_b32_e32 v44, v59
	v_mov_b32_e32 v45, v60
	v_mov_b32_e32 v46, v61
	v_mov_b32_e32 v47, v62
	v_mov_b32_e32 v48, v63
	v_mov_b32_e32 v51, v140
	v_mov_b32_e32 v52, v141
	v_mov_b32_e32 v53, v142
	v_mov_b32_e32 v54, v143
	v_mov_b32_e32 v55, v144
	v_mov_b32_e32 v56, v145
	v_mov_b32_e32 v57, v146
	v_mov_b32_e32 v58, v147
	v_mov_b32_e32 v59, v150
	v_mov_b32_e32 v60, v151
	v_mov_b32_e32 v61, v152
	v_mov_b32_e32 v62, v153
	v_mov_b32_e32 v63, v154
	v_mov_b32_e32 v64, v155
	v_mov_b32_e32 v50, v138
	v_mov_b32_e32 v34, v139
.LBB0_194:
	v_exp_f32_e32 v50, v50
	v_exp_f32_e32 v51, v51
	v_exp_f32_e32 v52, v52
	v_exp_f32_e32 v53, v53
	v_exp_f32_e32 v54, v54
	v_exp_f32_e32 v55, v55
	v_exp_f32_e32 v56, v56
	v_exp_f32_e32 v57, v57
	v_cvt_pk_bf16_f32 v136, v50, v51
	v_cvt_pk_bf16_f32 v137, v52, v53
	v_cvt_pk_bf16_f32 v138, v54, v55
	v_cvt_pk_bf16_f32 v139, v56, v57
	v_exp_f32_e32 v58, v58
	v_exp_f32_e32 v59, v59
	s_waitcnt lgkmcnt(0)
	v_mfma_f32_32x32x16_bf16 v[2:17], v[118:121], v[136:139], v[2:17]
	v_exp_f32_e32 v60, v60
	v_exp_f32_e32 v61, v61
	v_exp_f32_e32 v62, v62
	v_exp_f32_e32 v63, v63
	v_exp_f32_e32 v64, v64
	v_exp_f32_e32 v65, v65
	v_cvt_pk_bf16_f32 v140, v58, v59
	v_mfma_f32_32x32x16_bf16 v[18:33], v[102:105], v[136:139], v[18:33]
	v_cvt_pk_bf16_f32 v141, v60, v61
	v_cvt_pk_bf16_f32 v142, v62, v63
	v_cvt_pk_bf16_f32 v143, v64, v65
	v_exp_f32_e32 v34, v34
	v_exp_f32_e32 v35, v35
	v_exp_f32_e32 v36, v36
	v_exp_f32_e32 v37, v37
	v_mfma_f32_32x32x16_bf16 v[2:17], v[114:117], v[140:143], v[2:17]
	v_exp_f32_e32 v38, v38
	v_exp_f32_e32 v39, v39
	v_exp_f32_e32 v40, v40
	v_exp_f32_e32 v41, v41
	v_cvt_pk_bf16_f32 v144, v34, v35
	v_cvt_pk_bf16_f32 v145, v36, v37
	v_cvt_pk_bf16_f32 v146, v38, v39
	v_mfma_f32_32x32x16_bf16 v[18:33], v[98:101], v[140:143], v[18:33]
	v_cvt_pk_bf16_f32 v147, v40, v41
	v_exp_f32_e32 v42, v42
	v_exp_f32_e32 v43, v43
	v_exp_f32_e32 v44, v44
	v_exp_f32_e32 v45, v45
	v_exp_f32_e32 v46, v46
	v_exp_f32_e32 v47, v47
	v_mfma_f32_32x32x16_bf16 v[2:17], v[110:113], v[144:147], v[2:17]
	v_exp_f32_e32 v48, v48
	v_exp_f32_e32 v49, v49
	v_cvt_pk_bf16_f32 v150, v42, v43
	v_cvt_pk_bf16_f32 v151, v44, v45
	v_cvt_pk_bf16_f32 v152, v46, v47
	v_cvt_pk_bf16_f32 v153, v48, v49
	s_andn2_b64 vcc, exec, s[88:89]
	v_mfma_f32_32x32x16_bf16 v[18:33], v[90:93], v[144:147], v[18:33]
	v_mfma_f32_32x32x16_bf16 v[2:17], v[106:109], v[150:153], v[2:17]
	v_mfma_f32_32x32x16_bf16 v[18:33], v[94:97], v[150:153], v[18:33]
	s_cbranch_vccnz .LBB0_185
	ds_write_b128 v123, v[66:69]
	ds_write_b128 v122, v[78:81] offset:9216
	s_branch .LBB0_185
